# attention K/V staging via LDS-DMA into a 3-buffer LDS ring (no VGPR staging / ds_write), XOR-swizzled unpadded K image
# speedup vs baseline: 1.0422x; 1.0264x over previous
; #define LAS __attribute__((address_space(3)))
; __device__ __forceinline__ int opaque_tid() { int t = threadIdx.x; asm volatile("" : "+v"(t)); return t; }
; __device__ __forceinline__ int v_st_nat(int k, int c) { return ((k >> 3) * 2 + (c >> 5)) * 512 + ((k & 7) * 32 + (c & 31)) * 2; }
; __device__ __forceinline__ int v_rd_base(int lane) { return ((lane & 3) << 3) | (((lane >> 2) & 3) << 6) | (((lane >> 4) & 1) << 5) | (((lane >> 5) & 1) << 8); }
; #define AT_LOAD(K0, K1, V0, V1, T) do { const size_t e_ = (size_t)(128 * (T) + sr) * 64 + sc; \
;         K0 = *(const bf16x8*)(kcp + e_); V0 = *(const bf16x8*)(vcp + e_); K1 = *(const bf16x8*)(kcp + e_ + 64 * 64); V1 = *(const bf16x8*)(vcp + e_ + 64 * 64); } while (0)
; #define AT_STORE(K0, K1, V0, V1, BUF) do { *(LAS bf16x8*)(lds + AT_K + (BUF) * AT_KB + kst0) = K0; *(LAS bf16x8*)(lds + AT_K + (BUF) * AT_KB + kst1) = K1; \
;         *(LAS bf16x8*)(lds + AT_V + (BUF) * AT_VB + vst0) = V0; *(LAS bf16x8*)(lds + AT_V + (BUF) * AT_VB + vst1) = V1; } while (0)
; template <int VAR>
; __device__ __forceinline__ void attn_unit(const Args& a, int l, int b, int h, int qrow0  , bool ctxu, const bf16* Z, bf16* Y, LAS unsigned char* lds) {
;     const int tid = opaque_tid(), lane = tid & 63, wave = __builtin_amdgcn_readfirstlane(tid >> 6), r32 = lane & 31, hi = lane >> 5;
;     const int comp = wave >> 2, wq = wave & 3;
;     const int NT = ctxu ? 2 : 66;
;     const bf16* kcp = (const bf16*)(a.ws + WS_KC) + (size_t)(b * 4 + h) * 8448 * 64; const bf16* vcp = (const bf16*)(a.ws + WS_VC) + (size_t)(b * 4 + h) * 8448 * 64;
;     bf16x8 q0, q1;
;     { const bf16* qp = Z + (size_t)(qrow0 + wq * 32 + r32) * DIN + 512 + h * 64 + comp * 32 + hi * 8; q0 = *(const bf16x8*)(qp); q1 = *(const bf16x8*)(qp + 16); }
;     const int sr = tid >> 3, sc = (tid & 7) * 8;
;     const int kst0 = sr * 144 + sc * 2, kst1 = kst0 + 64 * 144, vst0 = v_st_nat(sr, sc), vst1 = v_st_nat(sr + 64, sc);
;     const int vb0 = (int)(unsigned)(uintptr_t)(lds + AT_V) + v_rd_base(lane);
;     LAS float* wsf = (LAS float*)(lds + AT_WS) + wave * 64;
;     f32x16 negm = f32x16{}, o0 = f32x16{}, o1 = f32x16{}, lacc = f32x16{};
;     float m = 0.f;
;     bf16x8 ka0, ka1, va0, va1, kb0, kb1, vb0_, vb1_;
;     ...
;     AT_LOAD(ka0, ka1, va0, va1, 0); AT_LOAD(kb0, kb1, vb0_, vb1_, 1); AT_STORE(ka0, ka1, va0, va1, 0);
.LBB0_429:
	s_ashr_i32 s9, s8, 6
	s_add_i32 s14, s9, s17
	s_lshl_b32 s9, s14, 11
	s_lshl_b32 s8, s8, 7
	v_mov_b32_e32 v12, v219
	s_and_b32 s9, s9, 0xffffe000
	s_and_b32 s8, s8, 0x1f80
	s_or_b32 s12, s8, s9
	v_readfirstlane_b32 s29, v12
	s_ashr_i32 s8, s29, 8
	s_bfe_u32 s9, s29, 0x20006
	s_mul_i32 s15, s14, 0x108000
	v_readlane_b32 s16, v254, 11
	v_ashrrev_i32_e32 v0, 3, v12
	v_lshlrev_b32_e32 v13, 3, v12
	s_mul_hi_i32 s13, s14, 0x108000
	s_add_u32 s36, s16, s15
	v_readlane_b32 s16, v254, 12
	v_and_b32_e32 v228, 56, v13
	v_ashrrev_i32_e32 v1, 31, v0
	s_addc_u32 s37, s16, s13
	v_readlane_b32 s16, v254, 13
	v_lshlrev_b32_e32 v2, 1, v228
	v_lshlrev_b64 v[4:5], 7, v[0:1]
	s_add_u32 s38, s16, s15
	v_readlane_b32 s15, v254, 14
	v_or_b32_e32 v6, v4, v2
	v_mov_b32_e32 v7, v5
	s_addc_u32 s39, s15, s13
	v_lshl_add_u64 v[8:9], s[36:37], 0, v[6:7]
	v_lshl_add_u64 v[10:11], s[38:39], 0, v[6:7]
	v_add_co_u32_e32 v8, vcc, s62, v8
	s_lshl_b32 s13, s9, 5
	s_nop 0
	v_addc_co_u32_e32 v9, vcc, 0, v9, vcc
	v_add_co_u32_e32 v8, vcc, s62, v10
	v_and_b32_e32 v247, 31, v12
	s_nop 0
	v_addc_co_u32_e32 v9, vcc, 0, v11, vcc
	s_or_b32 s60, s13, s12
	v_or_b32_e32 v1, s60, v247
	v_mov_b64_e32 v[8:9], s[0:1]
	v_mad_i64_i32 v[8:9], s[12:13], v1, s30, v[8:9]
	s_lshl_b32 s12, s14, 6
	s_and_b32 s28, s12, 0xc0
	s_lshl_b32 s72, s28, 1
	s_lshl_b32 s12, s8, 5
	v_bfe_u32 v248, v12, 5, 1
	v_lshl_add_u64 v[8:9], v[8:9], 0, s[72:73]
	s_ashr_i32 s13, s12, 31
	v_lshl_add_u64 v[8:9], s[12:13], 1, v[8:9]
	v_lshlrev_b32_e32 v216, 4, v248
	s_mov_b64 s[48:49], 0x4000
	v_lshl_add_u64 v[8:9], v[8:9], 0, v[216:217]
	v_lshl_add_u64 v[6:7], v[6:7], 0, s[48:49]
	global_load_dwordx4 v[136:139], v[8:9], off offset:1024
	global_load_dwordx4 v[140:143], v[8:9], off offset:1056
	v_lshl_add_u64 v[8:9], s[36:37], 0, v[6:7]
	v_lshl_add_u64 v[6:7], s[38:39], 0, v[6:7]
	v_add_co_u32_e32 v8, vcc, s62, v8
	s_movk_i32 s15, 0x90
	s_nop 0
	v_addc_co_u32_e32 v9, vcc, 0, v9, vcc
	v_add_co_u32_e32 v6, vcc, s62, v6
	v_mad_u64_u32 v[2:3], s[12:13], v0, s15, v[2:3]
	s_nop 0
	v_addc_co_u32_e32 v7, vcc, 0, v7, vcc
	v_lshlrev_b32_e32 v10, 5, v0
	v_and_b32_e32 v11, 24, v13
	s_movk_i32 s13, 0xe0
	v_add_u32_e32 v0, 64, v0
	v_lshrrev_b32_e32 v1, 5, v12
	v_bfe_u32 v3, v13, 5, 1
	s_mov_b32 s12, 0x7ffffe
	v_and_or_b32 v6, v10, s13, v11
	v_lshrrev_b32_e32 v0, 2, v0
	v_and_or_b32 v1, v1, s12, v3
	v_lshlrev_b32_e32 v6, 1, v6
	v_and_or_b32 v0, v0, s12, v3
	v_and_b32_e32 v227, 63, v12
	v_lshl_or_b32 v1, v1, 9, v6
	v_lshl_or_b32 v0, v0, 9, v6
	v_lshlrev_b32_e32 v6, 4, v12
	v_lshlrev_b32_e32 v3, 3, v227
	v_and_b32_e32 v6, 0xc0, v6
	v_lshlrev_b32_e32 v7, 1, v12
	v_and_or_b32 v6, v3, 24, v6
	v_and_b32_e32 v7, 32, v7
	v_and_b32_e32 v3, 0x100, v3
	v_or3_b32 v3, v6, v7, v3
	s_add_i32 s12, 0, 0x9000
	v_add_u32_e32 v249, s12, v3
	s_and_b32 s12, s29, 0x3fffffc0
	s_lshl_b32 s12, s12, 2
	s_add_i32 s31, s12, 0
	s_lshl_b32 s12, s8, 6
	s_add_i32 s12, s12, 0
	v_add_u32_e32 v229, 0, v0
	v_mov_b32_e32 v0, s12
	s_add_i32 s12, 0, 0xd000
	v_add_u32_e32 v251, 0, v1
	v_mad_u32_u24 v16, v247, s15, v0
	v_add_u32_e32 v233, s12, v3
	v_mad_i64_i32 v[0:1], s[12:13], s14, v246, v[4:5]
	v_add_u32_e32 v250, 0, v2
	v_and_b32_e32 v2, 7, v12
	v_readlane_b32 s12, v255, 17
	v_lshl_or_b32 v0, v2, 4, v0
	v_readlane_b32 s13, v255, 18
	v_mov_b32_e32 v14, v217
	v_mov_b32_e32 v15, v217
	s_add_i32 s31, s31, 0x11000
	v_lshl_add_u64 v[230:231], s[12:13], 0, v[0:1]
	v_mov_b32_e32 v0, v217
	v_mov_b32_e32 v1, v217
	v_mov_b32_e32 v2, v217
	v_mov_b32_e32 v3, v217
	v_mov_b32_e32 v4, v217
	v_mov_b32_e32 v5, v217
	v_mov_b32_e32 v6, v217
	v_mov_b32_e32 v7, v217
	v_mov_b32_e32 v8, v217
	v_mov_b32_e32 v9, v217
	v_mov_b32_e32 v10, v217
	v_mov_b32_e32 v11, v217
	v_mov_b32_e32 v12, v217
	v_mov_b32_e32 v13, v217
	v_mov_b32_e32 v234, 0
	v_add_u32_e32 v235, v16, v216
	v_mov_b64_e32 v[30:31], v[14:15]
	s_waitcnt vmcnt(0)
	v_mov_b64_e32 v[46:47], v[14:15]
	v_cmp_gt_u32_e64 s[38:39], 32, v227
	v_lshl_add_u32 v232, v247, 2, s31
	s_mov_b64 s[36:37], 0
	s_mov_b32 s33, 0
	v_mov_b64_e32 v[28:29], v[12:13]
	v_mov_b64_e32 v[26:27], v[10:11]
	v_mov_b64_e32 v[24:25], v[8:9]
	v_mov_b64_e32 v[22:23], v[6:7]
	v_mov_b64_e32 v[20:21], v[4:5]
	v_mov_b64_e32 v[18:19], v[2:3]
	v_mov_b64_e32 v[16:17], v[0:1]
	v_mov_b64_e32 v[44:45], v[12:13]
	v_mov_b64_e32 v[42:43], v[10:11]
	v_mov_b64_e32 v[40:41], v[8:9]
	v_mov_b64_e32 v[38:39], v[6:7]
	v_mov_b64_e32 v[36:37], v[4:5]
	v_mov_b64_e32 v[34:35], v[2:3]
	v_mov_b64_e32 v[32:33], v[0:1]
	s_waitcnt vmcnt(0)
	v_mov_b32_e32 v64, 0
	v_mov_b32_e32 v65, v234
	v_mov_b32_e32 v66, v234
	v_mov_b32_e32 v67, v234
	v_mov_b32_e32 v68, v234
	v_mov_b32_e32 v69, v234
	v_mov_b32_e32 v70, v234
	v_mov_b32_e32 v71, v234
	v_mov_b32_e32 v72, v234
	v_mov_b32_e32 v73, v234
	v_mov_b32_e32 v74, v234
	v_mov_b32_e32 v75, v234
	v_mov_b32_e32 v76, v234
	v_mov_b32_e32 v77, v234
	v_mov_b32_e32 v78, v234
	v_mov_b32_e32 v48, 0
	v_readlane_b32 s14, v255, 19
	v_readlane_b32 s15, v255, 20
	s_branch .LBB0_431
; #define LAS __attribute__((address_space(3)))
; __device__ __forceinline__ int v_st_nat(int k, int c) { return ((k >> 3) * 2 + (c >> 5)) * 512 + ((k & 7) * 32 + (c & 31)) * 2; }
; __device__ __forceinline__ int v_rd_base(int lane) { return ((lane & 3) << 3) | (((lane >> 2) & 3) << 6) | (((lane >> 4) & 1) << 5) | (((lane >> 5) & 1) << 8); }
; #define AT_LOAD(K0, K1, V0, V1, T) do { const size_t e_ = (size_t)(128 * (T) + sr) * 64 + sc; \
;         K0 = *(const bf16x8*)(kcp + e_); V0 = *(const bf16x8*)(vcp + e_); K1 = *(const bf16x8*)(kcp + e_ + 64 * 64); V1 = *(const bf16x8*)(vcp + e_ + 64 * 64); } while (0)
; #define AT_STORE(K0, K1, V0, V1, BUF) do { *(LAS bf16x8*)(lds + AT_K + (BUF) * AT_KB + kst0) = K0; *(LAS bf16x8*)(lds + AT_K + (BUF) * AT_KB + kst1) = K1; \
;         *(LAS bf16x8*)(lds + AT_V + (BUF) * AT_VB + vst0) = V0; *(LAS bf16x8*)(lds + AT_V + (BUF) * AT_VB + vst1) = V1; } while (0)
; template <int VAR>
; __device__ __forceinline__ void attn_unit(const Args& a, int l, int b, int h, int qrow0  , bool ctxu, const bf16* Z, bf16* Y, LAS unsigned char* lds) {
;     ...
;     const int sr = tid >> 3, sc = (tid & 7) * 8;
;     const int kst0 = sr * 144 + sc * 2, kst1 = kst0 + 64 * 144, vst0 = v_st_nat(sr, sc), vst1 = v_st_nat(sr + 64, sc);
;     const int vb0 = (int)(unsigned)(uintptr_t)(lds + AT_V) + v_rd_base(lane);
;     LAS float* wsf = (LAS float*)(lds + AT_WS) + wave * 64;
;     f32x16 negm = f32x16{}, o0 = f32x16{}, o1 = f32x16{}, lacc = f32x16{};
;     float m = 0.f;
;     bf16x8 ka0, ka1, va0, va1, kb0, kb1, vb0_, vb1_;
;     ...
;     AT_LOAD(ka0, ka1, va0, va1, 0); AT_LOAD(kb0, kb1, vb0_, vb1_, 1); AT_STORE(ka0, ka1, va0, va1, 0);
;     const LAS unsigned char* Kb0 = lds + AT_K + comp * 64;
;     for (int t = 0; t < NT; t += 2) {
;         __syncthreads();
;         if (t + 2 < NT) AT_LOAD(ka0, ka1, va0, va1, t + 2);
;         attn_tile(Kb0, vb0, q0, q1, negm, m, o0, o1, lacc, t == 0, wsf, r32, hi);
.LBB0_431:
	v_mov_b32_e32 v79, 0
	v_readfirstlane_b32 s36, v230
	v_readfirstlane_b32 s37, v231
	s_mov_b64 s[94:95], -1
	s_mov_b32 s33, 0
	s_lshr_b32 s50, s29, 6
	s_lshl_b32 s51, s50, 10
	s_lshl_b32 s50, s50, 3
	v_lshrrev_b32_e32 v34, 3, v227
	v_add_u32_e32 v34, s50, v34
	v_bfe_u32 v35, v34, 1, 3
	v_and_b32_e32 v36, 7, v227
	v_xor_b32_e32 v36, v36, v35
	v_lshlrev_b32_e32 v34, 7, v34
	v_lshl_or_b32 v128, v36, 4, v34
	v_add_u32_e32 v129, 0x2000, v128
	v_bfe_u32 v34, v227, 2, 3
	v_add_u32_e32 v34, s50, v34
	v_lshrrev_b32_e32 v35, 5, v227
	v_and_b32_e32 v36, 3, v227
	v_lshlrev_b32_e32 v35, 6, v35
	v_lshl_or_b32 v35, v36, 4, v35
	v_lshl_or_b32 v130, v34, 7, v35
	v_add_u32_e32 v131, 0x2000, v130
	s_lshl_b32 s50, s8, 2
	v_add_u32_e32 v34, s50, v248
	v_bfe_u32 v35, v247, 1, 3
	v_xor_b32_e32 v34, v34, v35
	v_lshlrev_b32_e32 v35, 7, v247
	v_lshl_or_b32 v34, v34, 4, v35
	v_xor_b32_e32 v35, 32, v34
	v_mov_b32_e32 v132, v34
	v_mov_b32_e32 v133, v35
	v_add_u32_e32 v134, 0x8000, v34
	v_add_u32_e32 v135, 0x8000, v35
	v_add_u32_e32 v144, 0x11800, v34
	v_add_u32_e32 v145, 0x11800, v35
	v_add_u32_e32 v36, 0xffff7000, v249
	v_add_u32_e32 v146, 0x4000, v36
	v_add_u32_e32 v147, 0xc000, v36
	v_add_u32_e32 v148, 0x15800, v36
	s_sub_u32 s36, s36, s51
	s_subb_u32 s37, s37, 0
	s_add_u32 s48, s36, 0x1d200000
	s_addc_u32 s49, s37, 0
	s_add_u32 s36, s36, 0x1c000000
	s_addc_u32 s37, s37, 0
	s_cmp_eq_u32 s8, 1
	s_cbranch_scc0 .Lat_noprio
	s_setprio 1
.Lat_noprio:
	s_waitcnt lgkmcnt(0)
	s_barrier
	s_add_u32 m0, s51, 0x0
	s_nop 0
	global_load_lds_dwordx4 v128, s[36:37]
	s_add_u32 m0, s51, 0x2000
	s_nop 0
	global_load_lds_dwordx4 v129, s[36:37]
	s_add_u32 m0, s51, 0x4000
	s_nop 0
	global_load_lds_dwordx4 v130, s[48:49]
	s_add_u32 m0, s51, 0x6000
	s_nop 0
	global_load_lds_dwordx4 v131, s[48:49]
	s_add_u32 s36, s36, 0x4000
	s_addc_u32 s37, s37, 0
	s_add_u32 s48, s48, 0x4000
	s_addc_u32 s49, s49, 0
	s_add_u32 m0, s51, 0x8000
	s_nop 0
	global_load_lds_dwordx4 v128, s[36:37]
	s_add_u32 m0, s51, 0xa000
	s_nop 0
	global_load_lds_dwordx4 v129, s[36:37]
	s_add_u32 m0, s51, 0xc000
	s_nop 0
	global_load_lds_dwordx4 v130, s[48:49]
	s_add_u32 m0, s51, 0xe000
	s_nop 0
	global_load_lds_dwordx4 v131, s[48:49]
	s_add_u32 s36, s36, 0x4000
	s_addc_u32 s37, s37, 0
	s_add_u32 s48, s48, 0x4000
	s_addc_u32 s49, s49, 0
	s_waitcnt vmcnt(4)
	s_barrier
	s_add_u32 m0, s51, 0x11800
	s_nop 0
	global_load_lds_dwordx4 v128, s[36:37]
	s_add_u32 m0, s51, 0x13800
	s_nop 0
	global_load_lds_dwordx4 v129, s[36:37]
	s_add_u32 m0, s51, 0x15800
	s_nop 0
	global_load_lds_dwordx4 v130, s[48:49]
	s_add_u32 m0, s51, 0x17800
	s_nop 0
	global_load_lds_dwordx4 v131, s[48:49]
	s_add_u32 s36, s36, 0x4000
	s_addc_u32 s37, s37, 0
	s_add_u32 s48, s48, 0x4000
	s_addc_u32 s49, s49, 0
	ds_read_b128 v[48:51], v132 offset:0
	ds_read_b128 v[52:55], v133 offset:0
	ds_read_b128 v[56:59], v132 offset:4096
	ds_read_b128 v[60:63], v133 offset:4096
.Lat_loop:
	s_waitcnt lgkmcnt(0)
	v_mfma_f32_32x32x16_bf16 v[96:111], v[48:51], v[136:139], v[64:79]
	ds_read_b64_tr_b16 v[168:169], v146 offset:0
	ds_read_b64_tr_b16 v[170:171], v146 offset:1024
	ds_read_b64_tr_b16 v[172:173], v146 offset:512
	ds_read_b64_tr_b16 v[174:175], v146 offset:1536
	v_mfma_f32_32x32x16_bf16 v[96:111], v[52:55], v[140:143], v[96:111]
	ds_read_b64_tr_b16 v[176:177], v146 offset:2048
	ds_read_b64_tr_b16 v[178:179], v146 offset:3072
	ds_read_b64_tr_b16 v[180:181], v146 offset:2560
	ds_read_b64_tr_b16 v[182:183], v146 offset:3584
	v_mfma_f32_32x32x16_bf16 v[112:127], v[56:59], v[136:139], v[64:79]
	ds_read_b64_tr_b16 v[184:185], v146 offset:4096
	ds_read_b64_tr_b16 v[186:187], v146 offset:5120
	ds_read_b64_tr_b16 v[188:189], v146 offset:4608
	ds_read_b64_tr_b16 v[190:191], v146 offset:5632
	v_mfma_f32_32x32x16_bf16 v[112:127], v[60:63], v[140:143], v[112:127]
	ds_read_b64_tr_b16 v[192:193], v146 offset:6144
	ds_read_b64_tr_b16 v[194:195], v146 offset:7168
	ds_read_b64_tr_b16 v[196:197], v146 offset:6656
	ds_read_b64_tr_b16 v[198:199], v146 offset:7680
	ds_read_b128 v[80:83], v132 offset:8192
	ds_read_b128 v[84:87], v133 offset:8192
	ds_read_b128 v[88:91], v132 offset:12288
	ds_read_b128 v[92:95], v133 offset:12288
	v_max3_f32 v34, v96, v97, v98
	v_max3_f32 v35, v99, v100, v101
	v_max3_f32 v34, v34, v102, v103
	v_max3_f32 v35, v35, v104, v105
	v_max3_f32 v34, v34, v106, v107
	v_max3_f32 v35, v35, v108, v109
	v_max3_f32 v34, v34, v110, v111
	v_max3_f32 v35, v35, v112, v113
	v_max3_f32 v34, v34, v114, v115
	v_max3_f32 v35, v35, v116, v117
	v_max3_f32 v34, v34, v118, v119
	v_max3_f32 v35, v35, v120, v121
	v_max3_f32 v34, v34, v122, v123
	v_max3_f32 v35, v35, v124, v125
	v_max3_f32 v34, v34, v126, v127
	v_max_f32_e32 v34, v34, v35
	v_mov_b32_e32 v35, v34
	s_nop 1
	v_permlane32_swap_b32_e32 v34, v35
	v_max_f32_e32 v34, v34, v35
	s_cmp_lg_u64 s[94:95], 0
	s_cbranch_scc1 .Lat_rareg0
	v_cmp_lt_f32_e32 vcc, s4, v34
	s_cbranch_vccnz .Lat_rareg0
.Lat_backg0:
	v_exp_f32_e32 v96, v96
	v_exp_f32_e32 v97, v97
	v_exp_f32_e32 v98, v98
	v_exp_f32_e32 v99, v99
	v_exp_f32_e32 v100, v100
	v_exp_f32_e32 v101, v101
	v_exp_f32_e32 v102, v102
	v_exp_f32_e32 v103, v103
	v_cvt_pk_bf16_f32 v40, v96, v97
	v_cvt_pk_bf16_f32 v41, v98, v99
	v_cvt_pk_bf16_f32 v42, v100, v101
	v_cvt_pk_bf16_f32 v43, v102, v103
	v_pk_add_f32 v[32:33], v[32:33], v[96:97]
	v_pk_add_f32 v[32:33], v[32:33], v[98:99]
	v_pk_add_f32 v[32:33], v[32:33], v[100:101]
	v_pk_add_f32 v[32:33], v[32:33], v[102:103]
	s_waitcnt lgkmcnt(15)
	v_mfma_f32_32x32x16_bf16 v[0:15], v[40:43], v[168:171], v[0:15]
	v_exp_f32_e32 v104, v104
	v_exp_f32_e32 v105, v105
	v_exp_f32_e32 v106, v106
	v_exp_f32_e32 v107, v107
	v_mfma_f32_32x32x16_bf16 v[16:31], v[40:43], v[172:175], v[16:31]
	v_exp_f32_e32 v108, v108
	v_exp_f32_e32 v109, v109
	v_exp_f32_e32 v110, v110
	v_exp_f32_e32 v111, v111
	v_cvt_pk_bf16_f32 v44, v104, v105
	v_cvt_pk_bf16_f32 v45, v106, v107
	v_cvt_pk_bf16_f32 v46, v108, v109
	v_cvt_pk_bf16_f32 v47, v110, v111
	v_pk_add_f32 v[32:33], v[32:33], v[104:105]
	v_pk_add_f32 v[32:33], v[32:33], v[106:107]
	v_pk_add_f32 v[32:33], v[32:33], v[108:109]
	v_pk_add_f32 v[32:33], v[32:33], v[110:111]
	s_waitcnt lgkmcnt(12)
	v_mfma_f32_32x32x16_bf16 v[0:15], v[44:47], v[176:179], v[0:15]
	v_exp_f32_e32 v112, v112
	v_exp_f32_e32 v113, v113
	v_exp_f32_e32 v114, v114
	v_exp_f32_e32 v115, v115
	v_mfma_f32_32x32x16_bf16 v[16:31], v[44:47], v[180:183], v[16:31]
	v_exp_f32_e32 v116, v116
	v_exp_f32_e32 v117, v117
	v_exp_f32_e32 v118, v118
	v_exp_f32_e32 v119, v119
	v_cvt_pk_bf16_f32 v40, v112, v113
	v_cvt_pk_bf16_f32 v41, v114, v115
	v_cvt_pk_bf16_f32 v42, v116, v117
	v_cvt_pk_bf16_f32 v43, v118, v119
	v_pk_add_f32 v[32:33], v[32:33], v[112:113]
	v_pk_add_f32 v[32:33], v[32:33], v[114:115]
	v_pk_add_f32 v[32:33], v[32:33], v[116:117]
	v_pk_add_f32 v[32:33], v[32:33], v[118:119]
	s_waitcnt lgkmcnt(8)
	v_mfma_f32_32x32x16_bf16 v[0:15], v[40:43], v[184:187], v[0:15]
	v_exp_f32_e32 v120, v120
	v_exp_f32_e32 v121, v121
	v_exp_f32_e32 v122, v122
	v_exp_f32_e32 v123, v123
	v_mfma_f32_32x32x16_bf16 v[16:31], v[40:43], v[188:191], v[16:31]
	v_exp_f32_e32 v124, v124
	v_exp_f32_e32 v125, v125
	v_exp_f32_e32 v126, v126
	v_exp_f32_e32 v127, v127
	v_cvt_pk_bf16_f32 v44, v120, v121
	v_cvt_pk_bf16_f32 v45, v122, v123
	v_cvt_pk_bf16_f32 v46, v124, v125
	v_cvt_pk_bf16_f32 v47, v126, v127
	v_pk_add_f32 v[32:33], v[32:33], v[120:121]
	v_pk_add_f32 v[32:33], v[32:33], v[122:123]
	v_pk_add_f32 v[32:33], v[32:33], v[124:125]
	v_pk_add_f32 v[32:33], v[32:33], v[126:127]
	s_waitcnt lgkmcnt(4)
	v_mfma_f32_32x32x16_bf16 v[0:15], v[44:47], v[192:195], v[0:15]
	v_mfma_f32_32x32x16_bf16 v[16:31], v[44:47], v[196:199], v[16:31]
	s_waitcnt lgkmcnt(0)
	v_mfma_f32_32x32x16_bf16 v[96:111], v[80:83], v[136:139], v[64:79]
	ds_read_b64_tr_b16 v[168:169], v146 offset:8192
	ds_read_b64_tr_b16 v[170:171], v146 offset:9216
	ds_read_b64_tr_b16 v[172:173], v146 offset:8704
	ds_read_b64_tr_b16 v[174:175], v146 offset:9728
	v_mfma_f32_32x32x16_bf16 v[96:111], v[84:87], v[140:143], v[96:111]
	ds_read_b64_tr_b16 v[176:177], v146 offset:10240
	ds_read_b64_tr_b16 v[178:179], v146 offset:11264
	ds_read_b64_tr_b16 v[180:181], v146 offset:10752
	ds_read_b64_tr_b16 v[182:183], v146 offset:11776
	v_mfma_f32_32x32x16_bf16 v[112:127], v[88:91], v[136:139], v[64:79]
	ds_read_b64_tr_b16 v[184:185], v146 offset:12288
	ds_read_b64_tr_b16 v[186:187], v146 offset:13312
	ds_read_b64_tr_b16 v[188:189], v146 offset:12800
	ds_read_b64_tr_b16 v[190:191], v146 offset:13824
	v_mfma_f32_32x32x16_bf16 v[112:127], v[92:95], v[140:143], v[112:127]
	ds_read_b64_tr_b16 v[192:193], v146 offset:14336
	ds_read_b64_tr_b16 v[194:195], v146 offset:15360
	ds_read_b64_tr_b16 v[196:197], v146 offset:14848
	ds_read_b64_tr_b16 v[198:199], v146 offset:15872
	v_max3_f32 v34, v96, v97, v98
	v_max3_f32 v35, v99, v100, v101
	v_max3_f32 v34, v34, v102, v103
	v_max3_f32 v35, v35, v104, v105
	v_max3_f32 v34, v34, v106, v107
	v_max3_f32 v35, v35, v108, v109
	v_max3_f32 v34, v34, v110, v111
	s_nop 1
	v_max3_f32 v35, v35, v112, v113
	v_max3_f32 v34, v34, v114, v115
	v_max3_f32 v35, v35, v116, v117
	v_max3_f32 v34, v34, v118, v119
	v_max3_f32 v35, v35, v120, v121
	v_max3_f32 v34, v34, v122, v123
	v_max3_f32 v35, v35, v124, v125
	v_max3_f32 v34, v34, v126, v127
	v_max_f32_e32 v34, v34, v35
	v_mov_b32_e32 v35, v34
	s_nop 1
	v_permlane32_swap_b32_e32 v34, v35
	v_max_f32_e32 v34, v34, v35
	v_cmp_lt_f32_e32 vcc, s4, v34
	s_cbranch_vccnz .Lat_rareg1
; #define AT_LOAD(K0, K1, V0, V1, T) do { const size_t e_ = (size_t)(128 * (T) + sr) * 64 + sc; \
;         K0 = *(const bf16x8*)(kcp + e_); V0 = *(const bf16x8*)(vcp + e_); K1 = *(const bf16x8*)(kcp + e_ + 64 * 64); V1 = *(const bf16x8*)(vcp + e_ + 64 * 64); } while (0)
; #define AT_STORE(K0, K1, V0, V1, BUF) do { *(LAS bf16x8*)(lds + AT_K + (BUF) * AT_KB + kst0) = K0; *(LAS bf16x8*)(lds + AT_K + (BUF) * AT_KB + kst1) = K1; \
;         *(LAS bf16x8*)(lds + AT_V + (BUF) * AT_VB + vst0) = V0; *(LAS bf16x8*)(lds + AT_V + (BUF) * AT_VB + vst1) = V1; } while (0)
; template <int VAR>
; __device__ __forceinline__ void attn_unit(const Args& a, int l, int b, int h, int qrow0  , bool ctxu, const bf16* Z, bf16* Y, LAS unsigned char* lds) {
;     ...
;         __syncthreads();
;         if (t + 2 < NT) AT_LOAD(ka0, ka1, va0, va1, t + 2);
;         attn_tile(Kb0, vb0, q0, q1, negm, m, o0, o1, lacc, t == 0, wsf, r32, hi);
;         AT_STORE(kb0, kb1, vb0_, vb1_, 1);
;         __syncthreads();
;         if (t + 3 < NT) AT_LOAD(kb0, kb1, vb0_, vb1_, t + 3);
;         attn_tile(Kb0 + AT_KB, vb0 + AT_VB, q0, q1, negm, m, o0, o1, lacc, false, wsf, r32, hi);
;         if (t + 2 < NT) AT_STORE(ka0, ka1, va0, va1, 0);
.Lat_backg1:
	v_exp_f32_e32 v96, v96
	v_exp_f32_e32 v97, v97
	v_exp_f32_e32 v98, v98
	v_exp_f32_e32 v99, v99
	v_exp_f32_e32 v100, v100
	v_exp_f32_e32 v101, v101
	v_exp_f32_e32 v102, v102
	v_exp_f32_e32 v103, v103
	v_cvt_pk_bf16_f32 v40, v96, v97
	v_cvt_pk_bf16_f32 v41, v98, v99
	v_cvt_pk_bf16_f32 v42, v100, v101
	v_cvt_pk_bf16_f32 v43, v102, v103
	v_pk_add_f32 v[32:33], v[32:33], v[96:97]
	v_pk_add_f32 v[32:33], v[32:33], v[98:99]
	v_pk_add_f32 v[32:33], v[32:33], v[100:101]
	v_pk_add_f32 v[32:33], v[32:33], v[102:103]
	s_waitcnt lgkmcnt(12)
	v_mfma_f32_32x32x16_bf16 v[0:15], v[40:43], v[168:171], v[0:15]
	v_exp_f32_e32 v104, v104
	v_exp_f32_e32 v105, v105
	v_exp_f32_e32 v106, v106
	v_exp_f32_e32 v107, v107
	v_mfma_f32_32x32x16_bf16 v[16:31], v[40:43], v[172:175], v[16:31]
	v_exp_f32_e32 v108, v108
	v_exp_f32_e32 v109, v109
	v_exp_f32_e32 v110, v110
	v_exp_f32_e32 v111, v111
	v_cvt_pk_bf16_f32 v44, v104, v105
	v_cvt_pk_bf16_f32 v45, v106, v107
	v_cvt_pk_bf16_f32 v46, v108, v109
	v_cvt_pk_bf16_f32 v47, v110, v111
	v_pk_add_f32 v[32:33], v[32:33], v[104:105]
	v_pk_add_f32 v[32:33], v[32:33], v[106:107]
	v_pk_add_f32 v[32:33], v[32:33], v[108:109]
	v_pk_add_f32 v[32:33], v[32:33], v[110:111]
	s_waitcnt lgkmcnt(8)
	v_mfma_f32_32x32x16_bf16 v[0:15], v[44:47], v[176:179], v[0:15]
	v_exp_f32_e32 v112, v112
	v_exp_f32_e32 v113, v113
	v_exp_f32_e32 v114, v114
	v_exp_f32_e32 v115, v115
	v_mfma_f32_32x32x16_bf16 v[16:31], v[44:47], v[180:183], v[16:31]
	v_exp_f32_e32 v116, v116
	v_exp_f32_e32 v117, v117
	v_exp_f32_e32 v118, v118
	v_exp_f32_e32 v119, v119
	v_cvt_pk_bf16_f32 v40, v112, v113
	v_cvt_pk_bf16_f32 v41, v114, v115
	v_cvt_pk_bf16_f32 v42, v116, v117
	v_cvt_pk_bf16_f32 v43, v118, v119
	v_pk_add_f32 v[32:33], v[32:33], v[112:113]
	v_pk_add_f32 v[32:33], v[32:33], v[114:115]
	v_pk_add_f32 v[32:33], v[32:33], v[116:117]
	v_pk_add_f32 v[32:33], v[32:33], v[118:119]
	s_waitcnt lgkmcnt(4)
	v_mfma_f32_32x32x16_bf16 v[0:15], v[40:43], v[184:187], v[0:15]
	v_exp_f32_e32 v120, v120
	v_exp_f32_e32 v121, v121
	v_exp_f32_e32 v122, v122
	v_exp_f32_e32 v123, v123
	v_mfma_f32_32x32x16_bf16 v[16:31], v[40:43], v[188:191], v[16:31]
	v_exp_f32_e32 v124, v124
	v_exp_f32_e32 v125, v125
	v_exp_f32_e32 v126, v126
	v_exp_f32_e32 v127, v127
	v_cvt_pk_bf16_f32 v44, v120, v121
	v_cvt_pk_bf16_f32 v45, v122, v123
	v_cvt_pk_bf16_f32 v46, v124, v125
	v_cvt_pk_bf16_f32 v47, v126, v127
	v_pk_add_f32 v[32:33], v[32:33], v[120:121]
	v_pk_add_f32 v[32:33], v[32:33], v[122:123]
	v_pk_add_f32 v[32:33], v[32:33], v[124:125]
	v_pk_add_f32 v[32:33], v[32:33], v[126:127]
	s_waitcnt vmcnt(4)
	s_waitcnt lgkmcnt(0)
	s_barrier
	s_add_u32 m0, s51, 0x0
	s_nop 0
	global_load_lds_dwordx4 v128, s[36:37]
	s_add_u32 m0, s51, 0x2000
	s_nop 0
	global_load_lds_dwordx4 v129, s[36:37]
	s_add_u32 m0, s51, 0x4000
	s_nop 0
	global_load_lds_dwordx4 v130, s[48:49]
	s_add_u32 m0, s51, 0x6000
	s_nop 0
	global_load_lds_dwordx4 v131, s[48:49]
	s_add_u32 s36, s36, 0x4000
	s_addc_u32 s37, s37, 0
	s_add_u32 s48, s48, 0x4000
	s_addc_u32 s49, s49, 0
	ds_read_b128 v[48:51], v134 offset:0
	ds_read_b128 v[52:55], v135 offset:0
	ds_read_b128 v[56:59], v134 offset:4096
	ds_read_b128 v[60:63], v135 offset:4096
	v_mfma_f32_32x32x16_bf16 v[0:15], v[44:47], v[192:195], v[0:15]
	v_mfma_f32_32x32x16_bf16 v[16:31], v[44:47], v[196:199], v[16:31]
	s_waitcnt lgkmcnt(0)
	v_mfma_f32_32x32x16_bf16 v[96:111], v[48:51], v[136:139], v[64:79]
	ds_read_b64_tr_b16 v[168:169], v147 offset:0
	ds_read_b64_tr_b16 v[170:171], v147 offset:1024
	ds_read_b64_tr_b16 v[172:173], v147 offset:512
	ds_read_b64_tr_b16 v[174:175], v147 offset:1536
	v_mfma_f32_32x32x16_bf16 v[96:111], v[52:55], v[140:143], v[96:111]
	ds_read_b64_tr_b16 v[176:177], v147 offset:2048
	ds_read_b64_tr_b16 v[178:179], v147 offset:3072
	ds_read_b64_tr_b16 v[180:181], v147 offset:2560
	ds_read_b64_tr_b16 v[182:183], v147 offset:3584
	v_mfma_f32_32x32x16_bf16 v[112:127], v[56:59], v[136:139], v[64:79]
	ds_read_b64_tr_b16 v[184:185], v147 offset:4096
	ds_read_b64_tr_b16 v[186:187], v147 offset:5120
	ds_read_b64_tr_b16 v[188:189], v147 offset:4608
	ds_read_b64_tr_b16 v[190:191], v147 offset:5632
	v_mfma_f32_32x32x16_bf16 v[112:127], v[60:63], v[140:143], v[112:127]
	ds_read_b64_tr_b16 v[192:193], v147 offset:6144
	ds_read_b64_tr_b16 v[194:195], v147 offset:7168
	ds_read_b64_tr_b16 v[196:197], v147 offset:6656
	ds_read_b64_tr_b16 v[198:199], v147 offset:7680
	ds_read_b128 v[80:83], v134 offset:8192
	ds_read_b128 v[84:87], v135 offset:8192
	ds_read_b128 v[88:91], v134 offset:12288
	ds_read_b128 v[92:95], v135 offset:12288
	v_max3_f32 v34, v96, v97, v98
	v_max3_f32 v35, v99, v100, v101
	v_max3_f32 v34, v34, v102, v103
	v_max3_f32 v35, v35, v104, v105
	v_max3_f32 v34, v34, v106, v107
	v_max3_f32 v35, v35, v108, v109
	v_max3_f32 v34, v34, v110, v111
	v_max3_f32 v35, v35, v112, v113
	v_max3_f32 v34, v34, v114, v115
	v_max3_f32 v35, v35, v116, v117
	v_max3_f32 v34, v34, v118, v119
	v_max3_f32 v35, v35, v120, v121
	v_max3_f32 v34, v34, v122, v123
	v_max3_f32 v35, v35, v124, v125
	v_max3_f32 v34, v34, v126, v127
	v_max_f32_e32 v34, v34, v35
	v_mov_b32_e32 v35, v34
	s_nop 1
	v_permlane32_swap_b32_e32 v34, v35
	v_max_f32_e32 v34, v34, v35
	v_cmp_lt_f32_e32 vcc, s4, v34
	s_cbranch_vccnz .Lat_rareg2
.Lat_backg2:
	v_exp_f32_e32 v96, v96
	v_exp_f32_e32 v97, v97
	v_exp_f32_e32 v98, v98
	v_exp_f32_e32 v99, v99
	v_exp_f32_e32 v100, v100
	v_exp_f32_e32 v101, v101
	v_exp_f32_e32 v102, v102
	v_exp_f32_e32 v103, v103
	v_cvt_pk_bf16_f32 v40, v96, v97
	v_cvt_pk_bf16_f32 v41, v98, v99
	v_cvt_pk_bf16_f32 v42, v100, v101
	v_cvt_pk_bf16_f32 v43, v102, v103
	v_pk_add_f32 v[32:33], v[32:33], v[96:97]
	v_pk_add_f32 v[32:33], v[32:33], v[98:99]
	v_pk_add_f32 v[32:33], v[32:33], v[100:101]
	v_pk_add_f32 v[32:33], v[32:33], v[102:103]
	s_waitcnt lgkmcnt(15)
	v_mfma_f32_32x32x16_bf16 v[0:15], v[40:43], v[168:171], v[0:15]
	v_exp_f32_e32 v104, v104
	v_exp_f32_e32 v105, v105
	v_exp_f32_e32 v106, v106
	v_exp_f32_e32 v107, v107
	v_mfma_f32_32x32x16_bf16 v[16:31], v[40:43], v[172:175], v[16:31]
	v_exp_f32_e32 v108, v108
	v_exp_f32_e32 v109, v109
	v_exp_f32_e32 v110, v110
	v_exp_f32_e32 v111, v111
	v_cvt_pk_bf16_f32 v44, v104, v105
	v_cvt_pk_bf16_f32 v45, v106, v107
	v_cvt_pk_bf16_f32 v46, v108, v109
	v_cvt_pk_bf16_f32 v47, v110, v111
	v_pk_add_f32 v[32:33], v[32:33], v[104:105]
	v_pk_add_f32 v[32:33], v[32:33], v[106:107]
	v_pk_add_f32 v[32:33], v[32:33], v[108:109]
	v_pk_add_f32 v[32:33], v[32:33], v[110:111]
	s_waitcnt lgkmcnt(12)
	v_mfma_f32_32x32x16_bf16 v[0:15], v[44:47], v[176:179], v[0:15]
	v_exp_f32_e32 v112, v112
	v_exp_f32_e32 v113, v113
	v_exp_f32_e32 v114, v114
	v_exp_f32_e32 v115, v115
	v_mfma_f32_32x32x16_bf16 v[16:31], v[44:47], v[180:183], v[16:31]
	v_exp_f32_e32 v116, v116
	v_exp_f32_e32 v117, v117
	v_exp_f32_e32 v118, v118
	v_exp_f32_e32 v119, v119
	v_cvt_pk_bf16_f32 v40, v112, v113
	v_cvt_pk_bf16_f32 v41, v114, v115
	v_cvt_pk_bf16_f32 v42, v116, v117
	v_cvt_pk_bf16_f32 v43, v118, v119
	v_pk_add_f32 v[32:33], v[32:33], v[112:113]
	v_pk_add_f32 v[32:33], v[32:33], v[114:115]
	v_pk_add_f32 v[32:33], v[32:33], v[116:117]
	v_pk_add_f32 v[32:33], v[32:33], v[118:119]
	s_waitcnt lgkmcnt(8)
	v_mfma_f32_32x32x16_bf16 v[0:15], v[40:43], v[184:187], v[0:15]
	v_exp_f32_e32 v120, v120
	v_exp_f32_e32 v121, v121
	v_exp_f32_e32 v122, v122
	v_exp_f32_e32 v123, v123
	v_mfma_f32_32x32x16_bf16 v[16:31], v[40:43], v[188:191], v[16:31]
	v_exp_f32_e32 v124, v124
	v_exp_f32_e32 v125, v125
	v_exp_f32_e32 v126, v126
	v_exp_f32_e32 v127, v127
	v_cvt_pk_bf16_f32 v44, v120, v121
	v_cvt_pk_bf16_f32 v45, v122, v123
	v_cvt_pk_bf16_f32 v46, v124, v125
	v_cvt_pk_bf16_f32 v47, v126, v127
	v_pk_add_f32 v[32:33], v[32:33], v[120:121]
	v_pk_add_f32 v[32:33], v[32:33], v[122:123]
	v_pk_add_f32 v[32:33], v[32:33], v[124:125]
	v_pk_add_f32 v[32:33], v[32:33], v[126:127]
	s_waitcnt lgkmcnt(4)
	v_mfma_f32_32x32x16_bf16 v[0:15], v[44:47], v[192:195], v[0:15]
	v_mfma_f32_32x32x16_bf16 v[16:31], v[44:47], v[196:199], v[16:31]
	s_waitcnt lgkmcnt(0)
	v_mfma_f32_32x32x16_bf16 v[96:111], v[80:83], v[136:139], v[64:79]
	ds_read_b64_tr_b16 v[168:169], v147 offset:8192
	ds_read_b64_tr_b16 v[170:171], v147 offset:9216
	ds_read_b64_tr_b16 v[172:173], v147 offset:8704
	ds_read_b64_tr_b16 v[174:175], v147 offset:9728
	v_mfma_f32_32x32x16_bf16 v[96:111], v[84:87], v[140:143], v[96:111]
	ds_read_b64_tr_b16 v[176:177], v147 offset:10240
	ds_read_b64_tr_b16 v[178:179], v147 offset:11264
	ds_read_b64_tr_b16 v[180:181], v147 offset:10752
	ds_read_b64_tr_b16 v[182:183], v147 offset:11776
	v_mfma_f32_32x32x16_bf16 v[112:127], v[88:91], v[136:139], v[64:79]
	ds_read_b64_tr_b16 v[184:185], v147 offset:12288
	ds_read_b64_tr_b16 v[186:187], v147 offset:13312
	ds_read_b64_tr_b16 v[188:189], v147 offset:12800
	ds_read_b64_tr_b16 v[190:191], v147 offset:13824
	v_mfma_f32_32x32x16_bf16 v[112:127], v[92:95], v[140:143], v[112:127]
	ds_read_b64_tr_b16 v[192:193], v147 offset:14336
	ds_read_b64_tr_b16 v[194:195], v147 offset:15360
	ds_read_b64_tr_b16 v[196:197], v147 offset:14848
	ds_read_b64_tr_b16 v[198:199], v147 offset:15872
	v_max3_f32 v34, v96, v97, v98
	v_max3_f32 v35, v99, v100, v101
	v_max3_f32 v34, v34, v102, v103
	v_max3_f32 v35, v35, v104, v105
	v_max3_f32 v34, v34, v106, v107
	v_max3_f32 v35, v35, v108, v109
	v_max3_f32 v34, v34, v110, v111
	s_nop 1
	v_max3_f32 v35, v35, v112, v113
	v_max3_f32 v34, v34, v114, v115
	v_max3_f32 v35, v35, v116, v117
	v_max3_f32 v34, v34, v118, v119
	v_max3_f32 v35, v35, v120, v121
	v_max3_f32 v34, v34, v122, v123
	v_max3_f32 v35, v35, v124, v125
	v_max3_f32 v34, v34, v126, v127
	v_max_f32_e32 v34, v34, v35
	v_mov_b32_e32 v35, v34
	s_nop 1
	v_permlane32_swap_b32_e32 v34, v35
	v_max_f32_e32 v34, v34, v35
	v_cmp_lt_f32_e32 vcc, s4, v34
	s_cbranch_vccnz .Lat_rareg3
; #define AT_LOAD(K0, K1, V0, V1, T) do { const size_t e_ = (size_t)(128 * (T) + sr) * 64 + sc; \
;         K0 = *(const bf16x8*)(kcp + e_); V0 = *(const bf16x8*)(vcp + e_); K1 = *(const bf16x8*)(kcp + e_ + 64 * 64); V1 = *(const bf16x8*)(vcp + e_ + 64 * 64); } while (0)
; #define AT_STORE(K0, K1, V0, V1, BUF) do { *(LAS bf16x8*)(lds + AT_K + (BUF) * AT_KB + kst0) = K0; *(LAS bf16x8*)(lds + AT_K + (BUF) * AT_KB + kst1) = K1; \
;         *(LAS bf16x8*)(lds + AT_V + (BUF) * AT_VB + vst0) = V0; *(LAS bf16x8*)(lds + AT_V + (BUF) * AT_VB + vst1) = V1; } while (0)
; template <int VAR>
; __device__ __forceinline__ void attn_unit(const Args& a, int l, int b, int h, int qrow0  , bool ctxu, const bf16* Z, bf16* Y, LAS unsigned char* lds) {
;     ...
;         AT_STORE(kb0, kb1, vb0_, vb1_, 1);
;         __syncthreads();
;         if (t + 3 < NT) AT_LOAD(kb0, kb1, vb0_, vb1_, t + 3);
;         attn_tile(Kb0 + AT_KB, vb0 + AT_VB, q0, q1, negm, m, o0, o1, lacc, false, wsf, r32, hi);
;         if (t + 2 < NT) AT_STORE(ka0, ka1, va0, va1, 0);
.Lat_backg3:
	v_exp_f32_e32 v96, v96
	v_exp_f32_e32 v97, v97
	v_exp_f32_e32 v98, v98
	v_exp_f32_e32 v99, v99
	v_exp_f32_e32 v100, v100
	v_exp_f32_e32 v101, v101
	v_exp_f32_e32 v102, v102
	v_exp_f32_e32 v103, v103
	v_cvt_pk_bf16_f32 v40, v96, v97
	v_cvt_pk_bf16_f32 v41, v98, v99
	v_cvt_pk_bf16_f32 v42, v100, v101
	v_cvt_pk_bf16_f32 v43, v102, v103
	v_pk_add_f32 v[32:33], v[32:33], v[96:97]
	v_pk_add_f32 v[32:33], v[32:33], v[98:99]
	v_pk_add_f32 v[32:33], v[32:33], v[100:101]
	v_pk_add_f32 v[32:33], v[32:33], v[102:103]
	s_waitcnt lgkmcnt(12)
	v_mfma_f32_32x32x16_bf16 v[0:15], v[40:43], v[168:171], v[0:15]
	v_exp_f32_e32 v104, v104
	v_exp_f32_e32 v105, v105
	v_exp_f32_e32 v106, v106
	v_exp_f32_e32 v107, v107
	v_mfma_f32_32x32x16_bf16 v[16:31], v[40:43], v[172:175], v[16:31]
	v_exp_f32_e32 v108, v108
	v_exp_f32_e32 v109, v109
	v_exp_f32_e32 v110, v110
	v_exp_f32_e32 v111, v111
	v_cvt_pk_bf16_f32 v44, v104, v105
	v_cvt_pk_bf16_f32 v45, v106, v107
	v_cvt_pk_bf16_f32 v46, v108, v109
	v_cvt_pk_bf16_f32 v47, v110, v111
	v_pk_add_f32 v[32:33], v[32:33], v[104:105]
	v_pk_add_f32 v[32:33], v[32:33], v[106:107]
	v_pk_add_f32 v[32:33], v[32:33], v[108:109]
	v_pk_add_f32 v[32:33], v[32:33], v[110:111]
	s_waitcnt lgkmcnt(8)
	v_mfma_f32_32x32x16_bf16 v[0:15], v[44:47], v[176:179], v[0:15]
	v_exp_f32_e32 v112, v112
	v_exp_f32_e32 v113, v113
	v_exp_f32_e32 v114, v114
	v_exp_f32_e32 v115, v115
	v_mfma_f32_32x32x16_bf16 v[16:31], v[44:47], v[180:183], v[16:31]
	v_exp_f32_e32 v116, v116
	v_exp_f32_e32 v117, v117
	v_exp_f32_e32 v118, v118
	v_exp_f32_e32 v119, v119
	v_cvt_pk_bf16_f32 v40, v112, v113
	v_cvt_pk_bf16_f32 v41, v114, v115
	v_cvt_pk_bf16_f32 v42, v116, v117
	v_cvt_pk_bf16_f32 v43, v118, v119
	v_pk_add_f32 v[32:33], v[32:33], v[112:113]
	v_pk_add_f32 v[32:33], v[32:33], v[114:115]
	v_pk_add_f32 v[32:33], v[32:33], v[116:117]
	v_pk_add_f32 v[32:33], v[32:33], v[118:119]
	s_waitcnt lgkmcnt(4)
	v_mfma_f32_32x32x16_bf16 v[0:15], v[40:43], v[184:187], v[0:15]
	v_exp_f32_e32 v120, v120
	v_exp_f32_e32 v121, v121
	v_exp_f32_e32 v122, v122
	v_exp_f32_e32 v123, v123
	v_mfma_f32_32x32x16_bf16 v[16:31], v[40:43], v[188:191], v[16:31]
	v_exp_f32_e32 v124, v124
	v_exp_f32_e32 v125, v125
	v_exp_f32_e32 v126, v126
	v_exp_f32_e32 v127, v127
	v_cvt_pk_bf16_f32 v44, v120, v121
	v_cvt_pk_bf16_f32 v45, v122, v123
	v_cvt_pk_bf16_f32 v46, v124, v125
	v_cvt_pk_bf16_f32 v47, v126, v127
	v_pk_add_f32 v[32:33], v[32:33], v[120:121]
	v_pk_add_f32 v[32:33], v[32:33], v[122:123]
	v_pk_add_f32 v[32:33], v[32:33], v[124:125]
	v_pk_add_f32 v[32:33], v[32:33], v[126:127]
	s_waitcnt vmcnt(4)
	s_waitcnt lgkmcnt(0)
	s_barrier
	s_add_u32 m0, s51, 0x8000
	s_nop 0
	global_load_lds_dwordx4 v128, s[36:37]
	s_add_u32 m0, s51, 0xa000
	s_nop 0
	global_load_lds_dwordx4 v129, s[36:37]
	s_add_u32 m0, s51, 0xc000
	s_nop 0
	global_load_lds_dwordx4 v130, s[48:49]
	s_add_u32 m0, s51, 0xe000
	s_nop 0
	global_load_lds_dwordx4 v131, s[48:49]
	s_add_u32 s36, s36, 0x4000
	s_addc_u32 s37, s37, 0
	s_add_u32 s48, s48, 0x4000
	s_addc_u32 s49, s49, 0
	ds_read_b128 v[48:51], v144 offset:0
	ds_read_b128 v[52:55], v145 offset:0
	ds_read_b128 v[56:59], v144 offset:4096
	ds_read_b128 v[60:63], v145 offset:4096
	v_mfma_f32_32x32x16_bf16 v[0:15], v[44:47], v[192:195], v[0:15]
	v_mfma_f32_32x32x16_bf16 v[16:31], v[44:47], v[196:199], v[16:31]
	s_waitcnt lgkmcnt(0)
	v_mfma_f32_32x32x16_bf16 v[96:111], v[48:51], v[136:139], v[64:79]
	ds_read_b64_tr_b16 v[168:169], v148 offset:0
	ds_read_b64_tr_b16 v[170:171], v148 offset:1024
	ds_read_b64_tr_b16 v[172:173], v148 offset:512
	ds_read_b64_tr_b16 v[174:175], v148 offset:1536
	v_mfma_f32_32x32x16_bf16 v[96:111], v[52:55], v[140:143], v[96:111]
	ds_read_b64_tr_b16 v[176:177], v148 offset:2048
	ds_read_b64_tr_b16 v[178:179], v148 offset:3072
	ds_read_b64_tr_b16 v[180:181], v148 offset:2560
	ds_read_b64_tr_b16 v[182:183], v148 offset:3584
	v_mfma_f32_32x32x16_bf16 v[112:127], v[56:59], v[136:139], v[64:79]
	ds_read_b64_tr_b16 v[184:185], v148 offset:4096
	ds_read_b64_tr_b16 v[186:187], v148 offset:5120
	ds_read_b64_tr_b16 v[188:189], v148 offset:4608
	ds_read_b64_tr_b16 v[190:191], v148 offset:5632
	v_mfma_f32_32x32x16_bf16 v[112:127], v[60:63], v[140:143], v[112:127]
	ds_read_b64_tr_b16 v[192:193], v148 offset:6144
	ds_read_b64_tr_b16 v[194:195], v148 offset:7168
	ds_read_b64_tr_b16 v[196:197], v148 offset:6656
	ds_read_b64_tr_b16 v[198:199], v148 offset:7680
	ds_read_b128 v[80:83], v144 offset:8192
	ds_read_b128 v[84:87], v145 offset:8192
	ds_read_b128 v[88:91], v144 offset:12288
	ds_read_b128 v[92:95], v145 offset:12288
	v_max3_f32 v34, v96, v97, v98
	v_max3_f32 v35, v99, v100, v101
	v_max3_f32 v34, v34, v102, v103
	v_max3_f32 v35, v35, v104, v105
	v_max3_f32 v34, v34, v106, v107
	v_max3_f32 v35, v35, v108, v109
	v_max3_f32 v34, v34, v110, v111
	v_max3_f32 v35, v35, v112, v113
	v_max3_f32 v34, v34, v114, v115
	v_max3_f32 v35, v35, v116, v117
	v_max3_f32 v34, v34, v118, v119
	v_max3_f32 v35, v35, v120, v121
	v_max3_f32 v34, v34, v122, v123
	v_max3_f32 v35, v35, v124, v125
	v_max3_f32 v34, v34, v126, v127
	v_max_f32_e32 v34, v34, v35
	v_mov_b32_e32 v35, v34
	s_nop 1
	v_permlane32_swap_b32_e32 v34, v35
	v_max_f32_e32 v34, v34, v35
	v_cmp_lt_f32_e32 vcc, s4, v34
	s_cbranch_vccnz .Lat_rareg4
.Lat_backg4:
	v_exp_f32_e32 v96, v96
	v_exp_f32_e32 v97, v97
	v_exp_f32_e32 v98, v98
	v_exp_f32_e32 v99, v99
	v_exp_f32_e32 v100, v100
	v_exp_f32_e32 v101, v101
	v_exp_f32_e32 v102, v102
	v_exp_f32_e32 v103, v103
	v_cvt_pk_bf16_f32 v40, v96, v97
	v_cvt_pk_bf16_f32 v41, v98, v99
	v_cvt_pk_bf16_f32 v42, v100, v101
	v_cvt_pk_bf16_f32 v43, v102, v103
	v_pk_add_f32 v[32:33], v[32:33], v[96:97]
	v_pk_add_f32 v[32:33], v[32:33], v[98:99]
	v_pk_add_f32 v[32:33], v[32:33], v[100:101]
	v_pk_add_f32 v[32:33], v[32:33], v[102:103]
	s_waitcnt lgkmcnt(15)
	v_mfma_f32_32x32x16_bf16 v[0:15], v[40:43], v[168:171], v[0:15]
	v_exp_f32_e32 v104, v104
	v_exp_f32_e32 v105, v105
	v_exp_f32_e32 v106, v106
	v_exp_f32_e32 v107, v107
	v_mfma_f32_32x32x16_bf16 v[16:31], v[40:43], v[172:175], v[16:31]
	v_exp_f32_e32 v108, v108
	v_exp_f32_e32 v109, v109
	v_exp_f32_e32 v110, v110
	v_exp_f32_e32 v111, v111
	v_cvt_pk_bf16_f32 v44, v104, v105
	v_cvt_pk_bf16_f32 v45, v106, v107
	v_cvt_pk_bf16_f32 v46, v108, v109
	v_cvt_pk_bf16_f32 v47, v110, v111
	v_pk_add_f32 v[32:33], v[32:33], v[104:105]
	v_pk_add_f32 v[32:33], v[32:33], v[106:107]
	v_pk_add_f32 v[32:33], v[32:33], v[108:109]
	v_pk_add_f32 v[32:33], v[32:33], v[110:111]
	s_waitcnt lgkmcnt(12)
	v_mfma_f32_32x32x16_bf16 v[0:15], v[44:47], v[176:179], v[0:15]
	v_exp_f32_e32 v112, v112
	v_exp_f32_e32 v113, v113
	v_exp_f32_e32 v114, v114
	v_exp_f32_e32 v115, v115
	v_mfma_f32_32x32x16_bf16 v[16:31], v[44:47], v[180:183], v[16:31]
	v_exp_f32_e32 v116, v116
	v_exp_f32_e32 v117, v117
	v_exp_f32_e32 v118, v118
	v_exp_f32_e32 v119, v119
	v_cvt_pk_bf16_f32 v40, v112, v113
	v_cvt_pk_bf16_f32 v41, v114, v115
	v_cvt_pk_bf16_f32 v42, v116, v117
	v_cvt_pk_bf16_f32 v43, v118, v119
	v_pk_add_f32 v[32:33], v[32:33], v[112:113]
	v_pk_add_f32 v[32:33], v[32:33], v[114:115]
	v_pk_add_f32 v[32:33], v[32:33], v[116:117]
	v_pk_add_f32 v[32:33], v[32:33], v[118:119]
	s_waitcnt lgkmcnt(8)
	v_mfma_f32_32x32x16_bf16 v[0:15], v[40:43], v[184:187], v[0:15]
	v_exp_f32_e32 v120, v120
	v_exp_f32_e32 v121, v121
	v_exp_f32_e32 v122, v122
	v_exp_f32_e32 v123, v123
	v_mfma_f32_32x32x16_bf16 v[16:31], v[40:43], v[188:191], v[16:31]
	v_exp_f32_e32 v124, v124
	v_exp_f32_e32 v125, v125
	v_exp_f32_e32 v126, v126
	v_exp_f32_e32 v127, v127
	v_cvt_pk_bf16_f32 v44, v120, v121
	v_cvt_pk_bf16_f32 v45, v122, v123
	v_cvt_pk_bf16_f32 v46, v124, v125
	v_cvt_pk_bf16_f32 v47, v126, v127
	v_pk_add_f32 v[32:33], v[32:33], v[120:121]
	v_pk_add_f32 v[32:33], v[32:33], v[122:123]
	v_pk_add_f32 v[32:33], v[32:33], v[124:125]
	v_pk_add_f32 v[32:33], v[32:33], v[126:127]
	s_waitcnt lgkmcnt(4)
	v_mfma_f32_32x32x16_bf16 v[0:15], v[44:47], v[192:195], v[0:15]
	v_mfma_f32_32x32x16_bf16 v[16:31], v[44:47], v[196:199], v[16:31]
	s_waitcnt lgkmcnt(0)
	v_mfma_f32_32x32x16_bf16 v[96:111], v[80:83], v[136:139], v[64:79]
	ds_read_b64_tr_b16 v[168:169], v148 offset:8192
	ds_read_b64_tr_b16 v[170:171], v148 offset:9216
	ds_read_b64_tr_b16 v[172:173], v148 offset:8704
	ds_read_b64_tr_b16 v[174:175], v148 offset:9728
	v_mfma_f32_32x32x16_bf16 v[96:111], v[84:87], v[140:143], v[96:111]
	ds_read_b64_tr_b16 v[176:177], v148 offset:10240
	ds_read_b64_tr_b16 v[178:179], v148 offset:11264
	ds_read_b64_tr_b16 v[180:181], v148 offset:10752
	ds_read_b64_tr_b16 v[182:183], v148 offset:11776
	v_mfma_f32_32x32x16_bf16 v[112:127], v[88:91], v[136:139], v[64:79]
	ds_read_b64_tr_b16 v[184:185], v148 offset:12288
	ds_read_b64_tr_b16 v[186:187], v148 offset:13312
	ds_read_b64_tr_b16 v[188:189], v148 offset:12800
	ds_read_b64_tr_b16 v[190:191], v148 offset:13824
	v_mfma_f32_32x32x16_bf16 v[112:127], v[92:95], v[140:143], v[112:127]
	ds_read_b64_tr_b16 v[192:193], v148 offset:14336
	ds_read_b64_tr_b16 v[194:195], v148 offset:15360
	ds_read_b64_tr_b16 v[196:197], v148 offset:14848
	ds_read_b64_tr_b16 v[198:199], v148 offset:15872
	v_max3_f32 v34, v96, v97, v98
	v_max3_f32 v35, v99, v100, v101
	v_max3_f32 v34, v34, v102, v103
	v_max3_f32 v35, v35, v104, v105
	v_max3_f32 v34, v34, v106, v107
	v_max3_f32 v35, v35, v108, v109
	v_max3_f32 v34, v34, v110, v111
	s_nop 1
	v_max3_f32 v35, v35, v112, v113
	v_max3_f32 v34, v34, v114, v115
	v_max3_f32 v35, v35, v116, v117
	v_max3_f32 v34, v34, v118, v119
	v_max3_f32 v35, v35, v120, v121
	v_max3_f32 v34, v34, v122, v123
	v_max3_f32 v35, v35, v124, v125
	v_max3_f32 v34, v34, v126, v127
	v_max_f32_e32 v34, v34, v35
	v_mov_b32_e32 v35, v34
	s_nop 1
	v_permlane32_swap_b32_e32 v34, v35
	v_max_f32_e32 v34, v34, v35
	v_cmp_lt_f32_e32 vcc, s4, v34
	s_cbranch_vccnz .Lat_rareg5
; #define AT_LOAD(K0, K1, V0, V1, T) do { const size_t e_ = (size_t)(128 * (T) + sr) * 64 + sc; \
;         K0 = *(const bf16x8*)(kcp + e_); V0 = *(const bf16x8*)(vcp + e_); K1 = *(const bf16x8*)(kcp + e_ + 64 * 64); V1 = *(const bf16x8*)(vcp + e_ + 64 * 64); } while (0)
; #define AT_STORE(K0, K1, V0, V1, BUF) do { *(LAS bf16x8*)(lds + AT_K + (BUF) * AT_KB + kst0) = K0; *(LAS bf16x8*)(lds + AT_K + (BUF) * AT_KB + kst1) = K1; \
;         *(LAS bf16x8*)(lds + AT_V + (BUF) * AT_VB + vst0) = V0; *(LAS bf16x8*)(lds + AT_V + (BUF) * AT_VB + vst1) = V1; } while (0)
; template <int VAR>
; __device__ __forceinline__ void attn_unit(const Args& a, int l, int b, int h, int qrow0  , bool ctxu, const bf16* Z, bf16* Y, LAS unsigned char* lds) {
;     ...
;     for (int t = 0; t < NT; t += 2) {
;         __syncthreads();
;         if (t + 2 < NT) AT_LOAD(ka0, ka1, va0, va1, t + 2);
;         attn_tile(Kb0, vb0, q0, q1, negm, m, o0, o1, lacc, t == 0, wsf, r32, hi);
;         AT_STORE(kb0, kb1, vb0_, vb1_, 1);
;         __syncthreads();
;         if (t + 3 < NT) AT_LOAD(kb0, kb1, vb0_, vb1_, t + 3);
;         attn_tile(Kb0 + AT_KB, vb0 + AT_VB, q0, q1, negm, m, o0, o1, lacc, false, wsf, r32, hi);
;         if (t + 2 < NT) AT_STORE(ka0, ka1, va0, va1, 0);
;     }
.Lat_backg5:
	v_exp_f32_e32 v96, v96
	v_exp_f32_e32 v97, v97
	v_exp_f32_e32 v98, v98
	v_exp_f32_e32 v99, v99
	v_exp_f32_e32 v100, v100
	v_exp_f32_e32 v101, v101
	v_exp_f32_e32 v102, v102
	v_exp_f32_e32 v103, v103
	v_cvt_pk_bf16_f32 v40, v96, v97
	v_cvt_pk_bf16_f32 v41, v98, v99
	v_cvt_pk_bf16_f32 v42, v100, v101
	v_cvt_pk_bf16_f32 v43, v102, v103
	v_pk_add_f32 v[32:33], v[32:33], v[96:97]
	v_pk_add_f32 v[32:33], v[32:33], v[98:99]
	v_pk_add_f32 v[32:33], v[32:33], v[100:101]
	v_pk_add_f32 v[32:33], v[32:33], v[102:103]
	s_waitcnt lgkmcnt(12)
	v_mfma_f32_32x32x16_bf16 v[0:15], v[40:43], v[168:171], v[0:15]
	v_exp_f32_e32 v104, v104
	v_exp_f32_e32 v105, v105
	v_exp_f32_e32 v106, v106
	v_exp_f32_e32 v107, v107
	v_mfma_f32_32x32x16_bf16 v[16:31], v[40:43], v[172:175], v[16:31]
	v_exp_f32_e32 v108, v108
	v_exp_f32_e32 v109, v109
	v_exp_f32_e32 v110, v110
	v_exp_f32_e32 v111, v111
	v_cvt_pk_bf16_f32 v44, v104, v105
	v_cvt_pk_bf16_f32 v45, v106, v107
	v_cvt_pk_bf16_f32 v46, v108, v109
	v_cvt_pk_bf16_f32 v47, v110, v111
	v_pk_add_f32 v[32:33], v[32:33], v[104:105]
	v_pk_add_f32 v[32:33], v[32:33], v[106:107]
	v_pk_add_f32 v[32:33], v[32:33], v[108:109]
	v_pk_add_f32 v[32:33], v[32:33], v[110:111]
	s_waitcnt lgkmcnt(8)
	v_mfma_f32_32x32x16_bf16 v[0:15], v[44:47], v[176:179], v[0:15]
	v_exp_f32_e32 v112, v112
	v_exp_f32_e32 v113, v113
	v_exp_f32_e32 v114, v114
	v_exp_f32_e32 v115, v115
	v_mfma_f32_32x32x16_bf16 v[16:31], v[44:47], v[180:183], v[16:31]
	v_exp_f32_e32 v116, v116
	v_exp_f32_e32 v117, v117
	v_exp_f32_e32 v118, v118
	v_exp_f32_e32 v119, v119
	v_cvt_pk_bf16_f32 v40, v112, v113
	v_cvt_pk_bf16_f32 v41, v114, v115
	v_cvt_pk_bf16_f32 v42, v116, v117
	v_cvt_pk_bf16_f32 v43, v118, v119
	v_pk_add_f32 v[32:33], v[32:33], v[112:113]
	v_pk_add_f32 v[32:33], v[32:33], v[114:115]
	v_pk_add_f32 v[32:33], v[32:33], v[116:117]
	v_pk_add_f32 v[32:33], v[32:33], v[118:119]
	s_waitcnt lgkmcnt(4)
	v_mfma_f32_32x32x16_bf16 v[0:15], v[40:43], v[184:187], v[0:15]
	v_exp_f32_e32 v120, v120
	v_exp_f32_e32 v121, v121
	v_exp_f32_e32 v122, v122
	v_exp_f32_e32 v123, v123
	v_mfma_f32_32x32x16_bf16 v[16:31], v[40:43], v[188:191], v[16:31]
	v_exp_f32_e32 v124, v124
	v_exp_f32_e32 v125, v125
	v_exp_f32_e32 v126, v126
	v_exp_f32_e32 v127, v127
	v_cvt_pk_bf16_f32 v44, v120, v121
	v_cvt_pk_bf16_f32 v45, v122, v123
	v_cvt_pk_bf16_f32 v46, v124, v125
	v_cvt_pk_bf16_f32 v47, v126, v127
	v_pk_add_f32 v[32:33], v[32:33], v[120:121]
	v_pk_add_f32 v[32:33], v[32:33], v[122:123]
	v_pk_add_f32 v[32:33], v[32:33], v[124:125]
	v_pk_add_f32 v[32:33], v[32:33], v[126:127]
	s_waitcnt vmcnt(4)
	s_waitcnt lgkmcnt(0)
	s_barrier
	s_add_u32 m0, s51, 0x11800
	s_nop 0
	global_load_lds_dwordx4 v128, s[36:37]
	s_add_u32 m0, s51, 0x13800
	s_nop 0
	global_load_lds_dwordx4 v129, s[36:37]
	s_add_u32 m0, s51, 0x15800
	s_nop 0
	global_load_lds_dwordx4 v130, s[48:49]
	s_add_u32 m0, s51, 0x17800
	s_nop 0
	global_load_lds_dwordx4 v131, s[48:49]
	s_add_u32 s36, s36, 0x4000
	s_addc_u32 s37, s37, 0
	s_add_u32 s48, s48, 0x4000
	s_addc_u32 s49, s49, 0
	ds_read_b128 v[48:51], v132 offset:0
	ds_read_b128 v[52:55], v133 offset:0
	ds_read_b128 v[56:59], v132 offset:4096
	ds_read_b128 v[60:63], v133 offset:4096
	v_mfma_f32_32x32x16_bf16 v[0:15], v[44:47], v[192:195], v[0:15]
	v_mfma_f32_32x32x16_bf16 v[16:31], v[44:47], v[196:199], v[16:31]
	s_add_u32 s33, s33, 1
	s_cmp_lt_u32 s33, 21
	s_cbranch_scc1 .Lat_loop
	s_waitcnt lgkmcnt(0)
	v_mfma_f32_32x32x16_bf16 v[96:111], v[48:51], v[136:139], v[64:79]
	ds_read_b64_tr_b16 v[168:169], v146 offset:0
	ds_read_b64_tr_b16 v[170:171], v146 offset:1024
	ds_read_b64_tr_b16 v[172:173], v146 offset:512
	ds_read_b64_tr_b16 v[174:175], v146 offset:1536
	v_mfma_f32_32x32x16_bf16 v[96:111], v[52:55], v[140:143], v[96:111]
	ds_read_b64_tr_b16 v[176:177], v146 offset:2048
	ds_read_b64_tr_b16 v[178:179], v146 offset:3072
	ds_read_b64_tr_b16 v[180:181], v146 offset:2560
	ds_read_b64_tr_b16 v[182:183], v146 offset:3584
	v_mfma_f32_32x32x16_bf16 v[112:127], v[56:59], v[136:139], v[64:79]
	ds_read_b64_tr_b16 v[184:185], v146 offset:4096
	ds_read_b64_tr_b16 v[186:187], v146 offset:5120
	ds_read_b64_tr_b16 v[188:189], v146 offset:4608
	ds_read_b64_tr_b16 v[190:191], v146 offset:5632
	v_mfma_f32_32x32x16_bf16 v[112:127], v[60:63], v[140:143], v[112:127]
	ds_read_b64_tr_b16 v[192:193], v146 offset:6144
	ds_read_b64_tr_b16 v[194:195], v146 offset:7168
	ds_read_b64_tr_b16 v[196:197], v146 offset:6656
	ds_read_b64_tr_b16 v[198:199], v146 offset:7680
	ds_read_b128 v[80:83], v132 offset:8192
	ds_read_b128 v[84:87], v133 offset:8192
	ds_read_b128 v[88:91], v132 offset:12288
	ds_read_b128 v[92:95], v133 offset:12288
	v_max3_f32 v34, v96, v97, v98
	v_max3_f32 v35, v99, v100, v101
	v_max3_f32 v34, v34, v102, v103
	v_max3_f32 v35, v35, v104, v105
	v_max3_f32 v34, v34, v106, v107
	v_max3_f32 v35, v35, v108, v109
	v_max3_f32 v34, v34, v110, v111
	v_max3_f32 v35, v35, v112, v113
	v_max3_f32 v34, v34, v114, v115
	v_max3_f32 v35, v35, v116, v117
	v_max3_f32 v34, v34, v118, v119
	v_max3_f32 v35, v35, v120, v121
	v_max3_f32 v34, v34, v122, v123
	v_max3_f32 v35, v35, v124, v125
	v_max3_f32 v34, v34, v126, v127
	v_max_f32_e32 v34, v34, v35
	v_mov_b32_e32 v35, v34
	s_nop 1
	v_permlane32_swap_b32_e32 v34, v35
	v_max_f32_e32 v34, v34, v35
	v_cmp_lt_f32_e32 vcc, s4, v34
	s_cbranch_vccnz .Lat_rarez0

; #define AT_LOAD(K0, K1, V0, V1, T) do { const size_t e_ = (size_t)(128 * (T) + sr) * 64 + sc; \
;         K0 = *(const bf16x8*)(kcp + e_); V0 = *(const bf16x8*)(vcp + e_); K1 = *(const bf16x8*)(kcp + e_ + 64 * 64); V1 = *(const bf16x8*)(vcp + e_ + 64 * 64); } while (0)
; #define AT_STORE(K0, K1, V0, V1, BUF) do { *(LAS bf16x8*)(lds + AT_K + (BUF) * AT_KB + kst0) = K0; *(LAS bf16x8*)(lds + AT_K + (BUF) * AT_KB + kst1) = K1; \
;         *(LAS bf16x8*)(lds + AT_V + (BUF) * AT_VB + vst0) = V0; *(LAS bf16x8*)(lds + AT_V + (BUF) * AT_VB + vst1) = V1; } while (0)
; template <int VAR>
; __device__ __forceinline__ void attn_unit(const Args& a, int l, int b, int h, int qrow0  , bool ctxu, const bf16* Z, bf16* Y, LAS unsigned char* lds) {
;     ...
;     for (int t = 0; t < NT; t += 2) {
;         __syncthreads();
;         if (t + 2 < NT) AT_LOAD(ka0, ka1, va0, va1, t + 2);
;         attn_tile(Kb0, vb0, q0, q1, negm, m, o0, o1, lacc, t == 0, wsf, r32, hi);
;         AT_STORE(kb0, kb1, vb0_, vb1_, 1);
;         __syncthreads();
;         if (t + 3 < NT) AT_LOAD(kb0, kb1, vb0_, vb1_, t + 3);
;         attn_tile(Kb0 + AT_KB, vb0 + AT_VB, q0, q1, negm, m, o0, o1, lacc, false, wsf, r32, hi);
;         if (t + 2 < NT) AT_STORE(ka0, ka1, va0, va1, 0);
.Lat_backz1:
	v_exp_f32_e32 v96, v96
	v_exp_f32_e32 v97, v97
	v_exp_f32_e32 v98, v98
	v_exp_f32_e32 v99, v99
	v_exp_f32_e32 v100, v100
	v_exp_f32_e32 v101, v101
	v_exp_f32_e32 v102, v102
	v_exp_f32_e32 v103, v103
	v_cvt_pk_bf16_f32 v40, v96, v97
	v_cvt_pk_bf16_f32 v41, v98, v99
	v_cvt_pk_bf16_f32 v42, v100, v101
	v_cvt_pk_bf16_f32 v43, v102, v103
	v_pk_add_f32 v[32:33], v[32:33], v[96:97]
	v_pk_add_f32 v[32:33], v[32:33], v[98:99]
	v_pk_add_f32 v[32:33], v[32:33], v[100:101]
	v_pk_add_f32 v[32:33], v[32:33], v[102:103]
	s_waitcnt lgkmcnt(12)
	v_mfma_f32_32x32x16_bf16 v[0:15], v[40:43], v[168:171], v[0:15]
	v_exp_f32_e32 v104, v104
	v_exp_f32_e32 v105, v105
	v_exp_f32_e32 v106, v106
	v_exp_f32_e32 v107, v107
	v_mfma_f32_32x32x16_bf16 v[16:31], v[40:43], v[172:175], v[16:31]
	v_exp_f32_e32 v108, v108
	v_exp_f32_e32 v109, v109
	v_exp_f32_e32 v110, v110
	v_exp_f32_e32 v111, v111
	v_cvt_pk_bf16_f32 v44, v104, v105
	v_cvt_pk_bf16_f32 v45, v106, v107
	v_cvt_pk_bf16_f32 v46, v108, v109
	v_cvt_pk_bf16_f32 v47, v110, v111
	v_pk_add_f32 v[32:33], v[32:33], v[104:105]
	v_pk_add_f32 v[32:33], v[32:33], v[106:107]
	v_pk_add_f32 v[32:33], v[32:33], v[108:109]
	v_pk_add_f32 v[32:33], v[32:33], v[110:111]
	s_waitcnt lgkmcnt(8)
	v_mfma_f32_32x32x16_bf16 v[0:15], v[44:47], v[176:179], v[0:15]
	v_exp_f32_e32 v112, v112
	v_exp_f32_e32 v113, v113
	v_exp_f32_e32 v114, v114
	v_exp_f32_e32 v115, v115
	v_mfma_f32_32x32x16_bf16 v[16:31], v[44:47], v[180:183], v[16:31]
	v_exp_f32_e32 v116, v116
	v_exp_f32_e32 v117, v117
	v_exp_f32_e32 v118, v118
	v_exp_f32_e32 v119, v119
	v_cvt_pk_bf16_f32 v40, v112, v113
	v_cvt_pk_bf16_f32 v41, v114, v115
	v_cvt_pk_bf16_f32 v42, v116, v117
	v_cvt_pk_bf16_f32 v43, v118, v119
	v_pk_add_f32 v[32:33], v[32:33], v[112:113]
	v_pk_add_f32 v[32:33], v[32:33], v[114:115]
	v_pk_add_f32 v[32:33], v[32:33], v[116:117]
	v_pk_add_f32 v[32:33], v[32:33], v[118:119]
	s_waitcnt lgkmcnt(4)
	v_mfma_f32_32x32x16_bf16 v[0:15], v[40:43], v[184:187], v[0:15]
	v_exp_f32_e32 v120, v120
	v_exp_f32_e32 v121, v121
	v_exp_f32_e32 v122, v122
	v_exp_f32_e32 v123, v123
	v_mfma_f32_32x32x16_bf16 v[16:31], v[40:43], v[188:191], v[16:31]
	v_exp_f32_e32 v124, v124
	v_exp_f32_e32 v125, v125
	v_exp_f32_e32 v126, v126
	v_exp_f32_e32 v127, v127
	v_cvt_pk_bf16_f32 v44, v120, v121
	v_cvt_pk_bf16_f32 v45, v122, v123
	v_cvt_pk_bf16_f32 v46, v124, v125
	v_cvt_pk_bf16_f32 v47, v126, v127
	v_pk_add_f32 v[32:33], v[32:33], v[120:121]
	v_pk_add_f32 v[32:33], v[32:33], v[122:123]
	v_pk_add_f32 v[32:33], v[32:33], v[124:125]
	v_pk_add_f32 v[32:33], v[32:33], v[126:127]
	s_waitcnt vmcnt(4)
	s_waitcnt lgkmcnt(0)
	s_barrier
	ds_read_b128 v[48:51], v134 offset:0
	ds_read_b128 v[52:55], v135 offset:0
	ds_read_b128 v[56:59], v134 offset:4096
	ds_read_b128 v[60:63], v135 offset:4096
	v_mfma_f32_32x32x16_bf16 v[0:15], v[44:47], v[192:195], v[0:15]
	v_mfma_f32_32x32x16_bf16 v[16:31], v[44:47], v[196:199], v[16:31]
	s_waitcnt lgkmcnt(0)
	v_mfma_f32_32x32x16_bf16 v[96:111], v[48:51], v[136:139], v[64:79]
	ds_read_b64_tr_b16 v[168:169], v147 offset:0
	ds_read_b64_tr_b16 v[170:171], v147 offset:1024
	ds_read_b64_tr_b16 v[172:173], v147 offset:512
	ds_read_b64_tr_b16 v[174:175], v147 offset:1536
	v_mfma_f32_32x32x16_bf16 v[96:111], v[52:55], v[140:143], v[96:111]
	ds_read_b64_tr_b16 v[176:177], v147 offset:2048
	ds_read_b64_tr_b16 v[178:179], v147 offset:3072
	ds_read_b64_tr_b16 v[180:181], v147 offset:2560
	ds_read_b64_tr_b16 v[182:183], v147 offset:3584
	v_mfma_f32_32x32x16_bf16 v[112:127], v[56:59], v[136:139], v[64:79]
	ds_read_b64_tr_b16 v[184:185], v147 offset:4096
	ds_read_b64_tr_b16 v[186:187], v147 offset:5120
	ds_read_b64_tr_b16 v[188:189], v147 offset:4608
	ds_read_b64_tr_b16 v[190:191], v147 offset:5632
	v_mfma_f32_32x32x16_bf16 v[112:127], v[60:63], v[140:143], v[112:127]
	ds_read_b64_tr_b16 v[192:193], v147 offset:6144
	ds_read_b64_tr_b16 v[194:195], v147 offset:7168
	ds_read_b64_tr_b16 v[196:197], v147 offset:6656
	ds_read_b64_tr_b16 v[198:199], v147 offset:7680
	ds_read_b128 v[80:83], v134 offset:8192
	ds_read_b128 v[84:87], v135 offset:8192
	ds_read_b128 v[88:91], v134 offset:12288
	ds_read_b128 v[92:95], v135 offset:12288
	v_max3_f32 v34, v96, v97, v98
	v_max3_f32 v35, v99, v100, v101
	v_max3_f32 v34, v34, v102, v103
	v_max3_f32 v35, v35, v104, v105
	v_max3_f32 v34, v34, v106, v107
	v_max3_f32 v35, v35, v108, v109
	v_max3_f32 v34, v34, v110, v111
	v_max3_f32 v35, v35, v112, v113
	v_max3_f32 v34, v34, v114, v115
	v_max3_f32 v35, v35, v116, v117
	v_max3_f32 v34, v34, v118, v119
	v_max3_f32 v35, v35, v120, v121
	v_max3_f32 v34, v34, v122, v123
	v_max3_f32 v35, v35, v124, v125
	v_max3_f32 v34, v34, v126, v127
	v_max_f32_e32 v34, v34, v35
	v_mov_b32_e32 v35, v34
	s_nop 1
	v_permlane32_swap_b32_e32 v34, v35
	v_max_f32_e32 v34, v34, v35
	v_cmp_lt_f32_e32 vcc, s4, v34
	s_cbranch_vccnz .Lat_rarez2

.Lat_backz3:
	v_exp_f32_e32 v96, v96
	v_exp_f32_e32 v97, v97
	v_exp_f32_e32 v98, v98
	v_exp_f32_e32 v99, v99
	v_exp_f32_e32 v100, v100
	v_exp_f32_e32 v101, v101
	v_exp_f32_e32 v102, v102
	v_exp_f32_e32 v103, v103
	v_cvt_pk_bf16_f32 v40, v96, v97
	v_cvt_pk_bf16_f32 v41, v98, v99
	v_cvt_pk_bf16_f32 v42, v100, v101
	v_cvt_pk_bf16_f32 v43, v102, v103
	v_pk_add_f32 v[32:33], v[32:33], v[96:97]
	v_pk_add_f32 v[32:33], v[32:33], v[98:99]
	v_pk_add_f32 v[32:33], v[32:33], v[100:101]
	v_pk_add_f32 v[32:33], v[32:33], v[102:103]
	s_waitcnt lgkmcnt(12)
	v_mfma_f32_32x32x16_bf16 v[0:15], v[40:43], v[168:171], v[0:15]
	v_exp_f32_e32 v104, v104
	v_exp_f32_e32 v105, v105
	v_exp_f32_e32 v106, v106
	v_exp_f32_e32 v107, v107
	v_mfma_f32_32x32x16_bf16 v[16:31], v[40:43], v[172:175], v[16:31]
	v_exp_f32_e32 v108, v108
	v_exp_f32_e32 v109, v109
	v_exp_f32_e32 v110, v110
	v_exp_f32_e32 v111, v111
	v_cvt_pk_bf16_f32 v44, v104, v105
	v_cvt_pk_bf16_f32 v45, v106, v107
	v_cvt_pk_bf16_f32 v46, v108, v109
	v_cvt_pk_bf16_f32 v47, v110, v111
	v_pk_add_f32 v[32:33], v[32:33], v[104:105]
	v_pk_add_f32 v[32:33], v[32:33], v[106:107]
	v_pk_add_f32 v[32:33], v[32:33], v[108:109]
	v_pk_add_f32 v[32:33], v[32:33], v[110:111]
	s_waitcnt lgkmcnt(8)
	v_mfma_f32_32x32x16_bf16 v[0:15], v[44:47], v[176:179], v[0:15]
	v_exp_f32_e32 v112, v112
	v_exp_f32_e32 v113, v113
	v_exp_f32_e32 v114, v114
	v_exp_f32_e32 v115, v115
	v_mfma_f32_32x32x16_bf16 v[16:31], v[44:47], v[180:183], v[16:31]
	v_exp_f32_e32 v116, v116
	v_exp_f32_e32 v117, v117
	v_exp_f32_e32 v118, v118
	v_exp_f32_e32 v119, v119
	v_cvt_pk_bf16_f32 v40, v112, v113
	v_cvt_pk_bf16_f32 v41, v114, v115
	v_cvt_pk_bf16_f32 v42, v116, v117
	v_cvt_pk_bf16_f32 v43, v118, v119
	v_pk_add_f32 v[32:33], v[32:33], v[112:113]
	v_pk_add_f32 v[32:33], v[32:33], v[114:115]
	v_pk_add_f32 v[32:33], v[32:33], v[116:117]
	v_pk_add_f32 v[32:33], v[32:33], v[118:119]
	s_waitcnt lgkmcnt(4)
	v_mfma_f32_32x32x16_bf16 v[0:15], v[40:43], v[184:187], v[0:15]
	v_exp_f32_e32 v120, v120
	v_exp_f32_e32 v121, v121
	v_exp_f32_e32 v122, v122
	v_exp_f32_e32 v123, v123
	v_mfma_f32_32x32x16_bf16 v[16:31], v[40:43], v[188:191], v[16:31]
	v_exp_f32_e32 v124, v124
	v_exp_f32_e32 v125, v125
	v_exp_f32_e32 v126, v126
	v_exp_f32_e32 v127, v127
	v_cvt_pk_bf16_f32 v44, v120, v121
	v_cvt_pk_bf16_f32 v45, v122, v123
	v_cvt_pk_bf16_f32 v46, v124, v125
	v_cvt_pk_bf16_f32 v47, v126, v127
	v_pk_add_f32 v[32:33], v[32:33], v[120:121]
	v_pk_add_f32 v[32:33], v[32:33], v[122:123]
	v_pk_add_f32 v[32:33], v[32:33], v[124:125]
	v_pk_add_f32 v[32:33], v[32:33], v[126:127]
	s_waitcnt vmcnt(0)
	s_waitcnt lgkmcnt(0)
	s_barrier
	ds_read_b128 v[48:51], v144 offset:0
	ds_read_b128 v[52:55], v145 offset:0
	ds_read_b128 v[56:59], v144 offset:4096
	ds_read_b128 v[60:63], v145 offset:4096
	v_mfma_f32_32x32x16_bf16 v[0:15], v[44:47], v[192:195], v[0:15]
	v_mfma_f32_32x32x16_bf16 v[16:31], v[44:47], v[196:199], v[16:31]
	s_waitcnt lgkmcnt(0)
	v_mfma_f32_32x32x16_bf16 v[96:111], v[48:51], v[136:139], v[64:79]
	ds_read_b64_tr_b16 v[168:169], v148 offset:0
	ds_read_b64_tr_b16 v[170:171], v148 offset:1024
	ds_read_b64_tr_b16 v[172:173], v148 offset:512
	ds_read_b64_tr_b16 v[174:175], v148 offset:1536
	v_mfma_f32_32x32x16_bf16 v[96:111], v[52:55], v[140:143], v[96:111]
	ds_read_b64_tr_b16 v[176:177], v148 offset:2048
	ds_read_b64_tr_b16 v[178:179], v148 offset:3072
	ds_read_b64_tr_b16 v[180:181], v148 offset:2560
	ds_read_b64_tr_b16 v[182:183], v148 offset:3584
	v_mfma_f32_32x32x16_bf16 v[112:127], v[56:59], v[136:139], v[64:79]
	ds_read_b64_tr_b16 v[184:185], v148 offset:4096
	ds_read_b64_tr_b16 v[186:187], v148 offset:5120
	ds_read_b64_tr_b16 v[188:189], v148 offset:4608
	ds_read_b64_tr_b16 v[190:191], v148 offset:5632
	v_mfma_f32_32x32x16_bf16 v[112:127], v[60:63], v[140:143], v[112:127]
	ds_read_b64_tr_b16 v[192:193], v148 offset:6144
	ds_read_b64_tr_b16 v[194:195], v148 offset:7168
	ds_read_b64_tr_b16 v[196:197], v148 offset:6656
	ds_read_b64_tr_b16 v[198:199], v148 offset:7680
	ds_read_b128 v[80:83], v144 offset:8192
	ds_read_b128 v[84:87], v145 offset:8192
	ds_read_b128 v[88:91], v144 offset:12288
	ds_read_b128 v[92:95], v145 offset:12288
	v_max3_f32 v34, v96, v97, v98
	v_max3_f32 v35, v99, v100, v101
	v_max3_f32 v34, v34, v102, v103
	v_max3_f32 v35, v35, v104, v105
	v_max3_f32 v34, v34, v106, v107
	v_max3_f32 v35, v35, v108, v109
	v_max3_f32 v34, v34, v110, v111
	v_max3_f32 v35, v35, v112, v113
	v_max3_f32 v34, v34, v114, v115
	v_max3_f32 v35, v35, v116, v117
	v_max3_f32 v34, v34, v118, v119
	v_max3_f32 v35, v35, v120, v121
	v_max3_f32 v34, v34, v122, v123
	v_max3_f32 v35, v35, v124, v125
	v_max3_f32 v34, v34, v126, v127
	v_max_f32_e32 v34, v34, v35
	v_mov_b32_e32 v35, v34
	s_nop 1
	v_permlane32_swap_b32_e32 v34, v35
	v_max_f32_e32 v34, v34, v35
	v_cmp_lt_f32_e32 vcc, s4, v34
	s_cbranch_vccnz .Lat_rarez4

; __device__ __forceinline__ int crow(int r, int hi) { return (r & 3) + 8 * (r >> 2) + 4 * hi; }
; template <int VAR>
; __device__ __forceinline__ void attn_unit(const Args& a, int l, int b, int h, int qrow0  , bool ctxu, const bf16* Z, bf16* Y, LAS unsigned char* lds) {
;     ...
;     if (comp == 1) {
; #pragma unroll
;         for (int r = 0; r < 16; ++r) { const int qr = crow(r, hi); const float il = lam * __builtin_amdgcn_rcpf(lacc[r]); stg[qr * 64 + r32] = o0[r] * il; stg[qr * 64 + 32 + r32] = o1[r] * il; }
;     }
;     __syncthreads();
;     if (comp == 0) {
; #pragma unroll
;         for (int r = 0; r < 16; ++r) { const int qr = crow(r, hi); const float il = __builtin_amdgcn_rcpf(lacc[r]); o0[r] = o0[r] * il - stg[qr * 64 + r32]; o1[r] = o1[r] * il - stg[qr * 64 + 32 + r32]; }
.Lat_backz5:
	v_exp_f32_e32 v96, v96
	v_exp_f32_e32 v97, v97
	v_exp_f32_e32 v98, v98
	v_exp_f32_e32 v99, v99
	v_exp_f32_e32 v100, v100
	v_exp_f32_e32 v101, v101
	v_exp_f32_e32 v102, v102
	v_exp_f32_e32 v103, v103
	v_cvt_pk_bf16_f32 v40, v96, v97
	v_cvt_pk_bf16_f32 v41, v98, v99
	v_cvt_pk_bf16_f32 v42, v100, v101
	v_cvt_pk_bf16_f32 v43, v102, v103
	v_pk_add_f32 v[32:33], v[32:33], v[96:97]
	v_pk_add_f32 v[32:33], v[32:33], v[98:99]
	v_pk_add_f32 v[32:33], v[32:33], v[100:101]
	v_pk_add_f32 v[32:33], v[32:33], v[102:103]
	s_waitcnt lgkmcnt(12)
	v_mfma_f32_32x32x16_bf16 v[0:15], v[40:43], v[168:171], v[0:15]
	v_exp_f32_e32 v104, v104
	v_exp_f32_e32 v105, v105
	v_exp_f32_e32 v106, v106
	v_exp_f32_e32 v107, v107
	v_mfma_f32_32x32x16_bf16 v[16:31], v[40:43], v[172:175], v[16:31]
	v_exp_f32_e32 v108, v108
	v_exp_f32_e32 v109, v109
	v_exp_f32_e32 v110, v110
	v_exp_f32_e32 v111, v111
	v_cvt_pk_bf16_f32 v44, v104, v105
	v_cvt_pk_bf16_f32 v45, v106, v107
	v_cvt_pk_bf16_f32 v46, v108, v109
	v_cvt_pk_bf16_f32 v47, v110, v111
	v_pk_add_f32 v[32:33], v[32:33], v[104:105]
	v_pk_add_f32 v[32:33], v[32:33], v[106:107]
	v_pk_add_f32 v[32:33], v[32:33], v[108:109]
	v_pk_add_f32 v[32:33], v[32:33], v[110:111]
	s_waitcnt lgkmcnt(8)
	v_mfma_f32_32x32x16_bf16 v[0:15], v[44:47], v[176:179], v[0:15]
	v_exp_f32_e32 v112, v112
	v_exp_f32_e32 v113, v113
	v_exp_f32_e32 v114, v114
	v_exp_f32_e32 v115, v115
	v_mfma_f32_32x32x16_bf16 v[16:31], v[44:47], v[180:183], v[16:31]
	v_exp_f32_e32 v116, v116
	v_exp_f32_e32 v117, v117
	v_exp_f32_e32 v118, v118
	v_exp_f32_e32 v119, v119
	v_cvt_pk_bf16_f32 v40, v112, v113
	v_cvt_pk_bf16_f32 v41, v114, v115
	v_cvt_pk_bf16_f32 v42, v116, v117
	v_cvt_pk_bf16_f32 v43, v118, v119
	v_pk_add_f32 v[32:33], v[32:33], v[112:113]
	v_pk_add_f32 v[32:33], v[32:33], v[114:115]
	v_pk_add_f32 v[32:33], v[32:33], v[116:117]
	v_pk_add_f32 v[32:33], v[32:33], v[118:119]
	s_waitcnt lgkmcnt(4)
	v_mfma_f32_32x32x16_bf16 v[0:15], v[40:43], v[184:187], v[0:15]
	v_exp_f32_e32 v120, v120
	v_exp_f32_e32 v121, v121
	v_exp_f32_e32 v122, v122
	v_exp_f32_e32 v123, v123
	v_mfma_f32_32x32x16_bf16 v[16:31], v[40:43], v[188:191], v[16:31]
	v_exp_f32_e32 v124, v124
	v_exp_f32_e32 v125, v125
	v_exp_f32_e32 v126, v126
	v_exp_f32_e32 v127, v127
	v_cvt_pk_bf16_f32 v44, v120, v121
	v_cvt_pk_bf16_f32 v45, v122, v123
	v_cvt_pk_bf16_f32 v46, v124, v125
	v_cvt_pk_bf16_f32 v47, v126, v127
	v_pk_add_f32 v[32:33], v[32:33], v[120:121]
	v_pk_add_f32 v[32:33], v[32:33], v[122:123]
	v_pk_add_f32 v[32:33], v[32:33], v[124:125]
	v_pk_add_f32 v[32:33], v[32:33], v[126:127]
	s_waitcnt vmcnt(0)
	s_waitcnt lgkmcnt(0)
	s_barrier
	ds_read_b128 v[48:51], v132 offset:0
	ds_read_b128 v[52:55], v133 offset:0
	ds_read_b128 v[56:59], v132 offset:4096
	ds_read_b128 v[60:63], v133 offset:4096
	v_mfma_f32_32x32x16_bf16 v[0:15], v[44:47], v[192:195], v[0:15]
	v_mfma_f32_32x32x16_bf16 v[16:31], v[44:47], v[196:199], v[16:31]
	s_barrier
	v_add_f32_e32 v34, v32, v33
	v_add_u32_e32 v36, s31, v216
	v_mov_b32_e32 v35, v34
	s_nop 1
	v_permlane32_swap_b32_e32 v34, v35
	v_add_f32_e32 v37, v34, v35
	s_waitcnt lgkmcnt(0)
	ds_write_b32 v232, v37
	s_waitcnt lgkmcnt(0)
	v_mov_b32_e32 v48, v36
	ds_read_b128 v[32:35], v48 offset:0
	ds_read_b128 v[36:39], v48 offset:32
	ds_read_b128 v[40:43], v48 offset:64
	ds_read_b128 v[44:47], v48 offset:96
	s_waitcnt vmcnt(0) lgkmcnt(0)
	s_setprio 0
	s_branch .LBB0_459
.Lat_tramp117:
	s_branch .LBB0_117
.Lat_rareg0:
	s_cmp_eq_u64 s[94:95], 0
	s_cbranch_scc0 .Lat_first
	v_max_f32_e32 v34, 0, v34
	v_exp_f32_e64 v35, -v34
	v_add_f32_e32 v234, v234, v34
	v_add_u32_e32 v36, s31, v216
	ds_write_b32 v232, v35
	v_mul_f32_e32 v32, v32, v35
	v_mul_f32_e32 v33, v33, v35
	v_sub_f32_e32 v96, v96, v34
	v_sub_f32_e32 v97, v97, v34
	v_sub_f32_e32 v98, v98, v34
	v_sub_f32_e32 v99, v99, v34
	v_sub_f32_e32 v100, v100, v34
	v_sub_f32_e32 v101, v101, v34
	v_sub_f32_e32 v102, v102, v34
	v_sub_f32_e32 v103, v103, v34
	v_sub_f32_e32 v104, v104, v34
	v_sub_f32_e32 v105, v105, v34
	v_sub_f32_e32 v106, v106, v34
	v_sub_f32_e32 v107, v107, v34
	v_sub_f32_e32 v108, v108, v34
	v_sub_f32_e32 v109, v109, v34
	v_sub_f32_e32 v110, v110, v34
	v_sub_f32_e32 v111, v111, v34
	v_sub_f32_e32 v112, v112, v34
	v_sub_f32_e32 v113, v113, v34
	v_sub_f32_e32 v114, v114, v34
	v_sub_f32_e32 v115, v115, v34
	v_sub_f32_e32 v116, v116, v34
	v_sub_f32_e32 v117, v117, v34
	v_sub_f32_e32 v118, v118, v34
	v_sub_f32_e32 v119, v119, v34
	v_sub_f32_e32 v120, v120, v34
	v_sub_f32_e32 v121, v121, v34
	v_sub_f32_e32 v122, v122, v34
	v_sub_f32_e32 v123, v123, v34
	v_sub_f32_e32 v124, v124, v34
	v_sub_f32_e32 v125, v125, v34
	v_sub_f32_e32 v126, v126, v34
	v_sub_f32_e32 v127, v127, v34
	v_xor_b32_e32 v64, 0x80000000, v234
	v_mov_b32_e32 v65, v64
	v_mov_b32_e32 v66, v64
	v_mov_b32_e32 v67, v64
	v_mov_b32_e32 v68, v64
	v_mov_b32_e32 v69, v64
	v_mov_b32_e32 v70, v64
	v_mov_b32_e32 v71, v64
	v_mov_b32_e32 v72, v64
	v_mov_b32_e32 v73, v64
	v_mov_b32_e32 v74, v64
	v_mov_b32_e32 v75, v64
	v_mov_b32_e32 v76, v64
	v_mov_b32_e32 v77, v64
	v_mov_b32_e32 v78, v64
	v_mov_b32_e32 v79, v64
	s_waitcnt lgkmcnt(0)
	ds_read_b128 v[208:211], v36 offset:0
	ds_read_b128 v[212:215], v36 offset:32
	s_waitcnt lgkmcnt(0)
	v_mul_f32_e32 v0, v0, v208
	v_mul_f32_e32 v16, v16, v208
	v_mul_f32_e32 v1, v1, v209
	v_mul_f32_e32 v17, v17, v209
	v_mul_f32_e32 v2, v2, v210
	v_mul_f32_e32 v18, v18, v210
	v_mul_f32_e32 v3, v3, v211
	v_mul_f32_e32 v19, v19, v211
	v_mul_f32_e32 v4, v4, v212
	v_mul_f32_e32 v20, v20, v212
	v_mul_f32_e32 v5, v5, v213
	v_mul_f32_e32 v21, v21, v213
	v_mul_f32_e32 v6, v6, v214
	v_mul_f32_e32 v22, v22, v214
	v_mul_f32_e32 v7, v7, v215
	v_mul_f32_e32 v23, v23, v215
	ds_read_b128 v[208:211], v36 offset:64
	ds_read_b128 v[212:215], v36 offset:96
	s_waitcnt lgkmcnt(0)
	v_mul_f32_e32 v8, v8, v208
	v_mul_f32_e32 v24, v24, v208
	v_mul_f32_e32 v9, v9, v209
	v_mul_f32_e32 v25, v25, v209
	v_mul_f32_e32 v10, v10, v210
	v_mul_f32_e32 v26, v26, v210
	v_mul_f32_e32 v11, v11, v211
	v_mul_f32_e32 v27, v27, v211
	v_mul_f32_e32 v12, v12, v212
	v_mul_f32_e32 v28, v28, v212
	v_mul_f32_e32 v13, v13, v213
	v_mul_f32_e32 v29, v29, v213
	v_mul_f32_e32 v14, v14, v214
	v_mul_f32_e32 v30, v30, v214
	v_mul_f32_e32 v15, v15, v215
	v_mul_f32_e32 v31, v31, v215
	s_branch .Lat_backg0
